# scan inner loop hand-rescheduled: software-pipelined LDS operand reads, fully unrolled 16 steps
# speedup vs baseline: 1.0480x; 1.0480x over previous
; DI void scan_item(const Params& p, int b, int h, int half, char* smem, unsigned* pgen, unsigned kp) {
;     ...
;   __builtin_amdgcn_s_setprio(3);
; #pragma unroll 1
;   for (int c = 0; c < T / SC; c += 2) {
;     chunk(c, RA);
;     chunk(c + 1, RB);
;   }
;   __builtin_amdgcn_s_setprio(0);
;   __syncthreads();
; __global__ void __launch_bounds__(256, 2) fwd_megakernel(Params p) {
;     ...
;             for (int i = X.rank; i < 16; i += NS) scan_item(p, b, i >> 1, i & 1, smem, pbar + 1, kp);
.LBB0_680:
	s_setprio 0
	v_lshlrev_b32_e32 v34, 2, v173
	ds_read_b32 v198, v34 offset:32768
	ds_read_b32 v199, v34 offset:33792
	ds_read_b32 v200, v34 offset:34816
	ds_read_b32 v201, v34 offset:35840
	ds_read_b32 v202, v34 offset:36864
	ds_read_b32 v203, v34 offset:37888
	ds_read_b32 v230, v34 offset:38912
	ds_read_b32 v231, v34 offset:39936
	ds_read_b32 v232, v34 offset:40960
	ds_read_b32 v233, v34 offset:41984
	s_waitcnt lgkmcnt(0)
	v_readlane_b32 s4, v254, 24
	s_add_i32 s21, s21, s4
	v_readlane_b32 s4, v254, 25
	v_readlane_b32 s5, v254, 26
	s_xor_b64 s[8:9], s[8:9], s[4:5]
	s_cmp_gt_i32 s21, 15
	s_barrier
	s_cbranch_scc1 .LBB0_717

; DI float* aaptr(char* ws, size_t m) { return (float*)(ws + OFF_PROJ + (m >> 12) * SLAB + PROJ_B) + (m & 4095) * 512; }
; DI void scan_item(const Params& p, int b, int h, int half, char* smem, unsigned* pgen, unsigned kp) {
;     ...
;   auto prefetch = [&](int c, ScanRaw& R) {
;     const int t = c * SC + ls;
;     const size_t m = (size_t)b * T + t;
;     R.w = *(const float4*)(Wg + m * 512 + hc);
;     R.k = *(const float4*)(KPg + m * 512 + hc);
;     R.kk = *(const float4*)(KKg + m * 512 + hc);
;     R.a = *(const float4*)(aaptr(p.ws, m) + hc);
;     R.rc = *(const uint2*)(proj + prow(m) + R_OFF + hc);
;     R.vc = *(const uint2*)(proj + prow(m) + V_OFF + hc);
;     R.rp = make_uint2(0, 0); R.vp = make_uint2(0, 0);
;     if (t > 0) { R.rp = *(const uint2*)(proj + prow(m - 1) + R_OFF + hc); R.vp = *(const uint2*)(proj + prow(m - 1) + V_OFF + hc); }
;   };
;     ...
;   ScanRaw RA, RB;
;   prefetch(0, RA);
;   prefetch(1, RB);
;   __builtin_amdgcn_s_setprio(3);
; #pragma unroll 1
;   for (int c = 0; c < T / SC; c += 2) {
.LBB0_685:
	s_or_b64 exec, exec, s[16:17]
	v_lshl_add_u64 v[14:15], v[90:91], 0, v[34:35]
	s_waitcnt vmcnt(13)
	v_lshl_add_u64 v[18:19], v[92:93], 0, v[34:35]
	s_waitcnt vmcnt(12)
	v_lshl_add_u64 v[22:23], v[94:95], 0, v[34:35]
	s_waitcnt vmcnt(11)
	v_lshl_add_u64 v[30:31], v[96:97], 0, v[34:35]
	v_lshl_add_u64 v[36:37], v[98:99], 0, v[110:111]
	global_load_dwordx4 v[14:17], v[14:15], off
	s_nop 0
	global_load_dwordx4 v[18:21], v[18:19], off
	s_nop 0
	global_load_dwordx4 v[22:25], v[22:23], off
	s_nop 0
	global_load_dwordx4 v[30:33], v[30:31], off
	s_nop 0
	global_load_dwordx2 v[140:141], v[36:37], off offset:2560
	v_lshl_add_u64 v[36:37], v[100:101], 0, v[110:111]
	v_lshl_add_u64 v[38:39], v[102:103], 0, v[110:111]
	v_lshl_add_u64 v[40:41], v[104:105], 0, v[110:111]
	global_load_dwordx2 v[144:145], v[36:37], off
	global_load_dwordx2 v[146:147], v[38:39], off offset:2560
	global_load_dwordx2 v[148:149], v[40:41], off
	v_cndmask_b32_e64 v0, 0, 1, s[8:9]
	s_waitcnt vmcnt(18)
	v_lshl_add_u32 v160, v0, 7, v226
	s_and_b32 s16, s21, 1
	s_setprio 3
	v_readlane_b32 s18, v253, 4
	v_readlane_b32 s19, v253, 5
	s_ashr_i32 s11, s10, 31
	s_ashr_i32 s5, s4, 31
	v_lshl_add_u64 v[118:119], s[18:19], 0, v[34:35]
	s_lshl_b64 s[10:11], s[10:11], 2
	v_readlane_b32 s18, v253, 32
	v_readlane_b32 s19, v253, 33
	s_add_u32 s10, s18, s10
	v_lshl_add_u64 v[124:125], s[4:5], 2, v[106:107]
	s_addc_u32 s11, s19, s11
	s_lshl_b64 s[4:5], s[4:5], 1
	v_readlane_b32 s18, v254, 2
	v_readlane_b32 s19, v254, 3
	s_add_u32 s4, s18, s4
	v_or_b32_e32 v0, s16, v197
	s_addc_u32 s5, s19, s5
	s_lshl_b32 s16, s16, 6
	v_readlane_b32 s36, v252, 20
	s_add_u32 s4, s4, s16
	v_cmp_eq_u32_e64 s[22:23], 0, v0
	v_readlane_b32 s38, v252, 22
	v_readlane_b32 s39, v252, 23
	v_readlane_b32 s40, v252, 24
	v_readlane_b32 s41, v252, 25
	v_readlane_b32 s44, v252, 28
	v_readlane_b32 s45, v252, 29
	v_readlane_b32 s46, v252, 30
	v_readlane_b32 s47, v252, 31
	s_addc_u32 s5, s5, 0
	v_mov_b32_e32 v209, v1
	v_mov_b32_e32 v0, v1
	v_lshl_add_u64 v[120:121], s[0:1], 0, v[34:35]
	v_lshl_add_u64 v[122:123], s[2:3], 0, v[34:35]
	s_mov_b32 s25, 0
	v_lshl_add_u64 v[132:133], s[38:39], 0, v[34:35]
	v_lshl_add_u64 v[134:135], s[40:41], 0, v[34:35]
	v_lshl_add_u64 v[136:137], s[44:45], 0, v[34:35]
	v_lshl_add_u64 v[138:139], s[46:47], 0, v[34:35]
	v_lshl_add_u64 v[142:143], s[4:5], 0, v[208:209]
	v_mov_b64_e32 v[60:61], v[0:1]
	v_mov_b64_e32 v[62:63], v[0:1]
	v_mov_b64_e32 v[64:65], v[0:1]
	v_mov_b64_e32 v[66:67], v[0:1]
	v_readlane_b32 s37, v252, 21
	v_readlane_b32 s42, v252, 26
	v_readlane_b32 s43, v252, 27
	v_readlane_b32 s48, v252, 32
	v_readlane_b32 s49, v252, 33
	v_readlane_b32 s50, v252, 34
	v_readlane_b32 s51, v252, 35
	v_lshlrev_b32_e32 v34, 2, v173
	ds_write_b32 v34, v198 offset:32768
	ds_write_b32 v34, v199 offset:33792
	ds_write_b32 v34, v200 offset:34816
	ds_write_b32 v34, v201 offset:35840
	ds_write_b32 v34, v202 offset:36864
	ds_write_b32 v34, v203 offset:37888
	ds_write_b32 v34, v230 offset:38912
	ds_write_b32 v34, v231 offset:39936
	ds_write_b32 v34, v232 offset:40960
	ds_write_b32 v34, v233 offset:41984
	s_branch .LBB0_687

; DI float oct_sum(float v) { v += dpp_f<0xB1>(v); v += dpp_f<0x4E>(v); v += dpp_f<0x141>(v); return v; }
; DI void scan_item(const Params& p, int b, int h, int half, char* smem, unsigned* pgen, unsigned kp) {
;     ...
; #pragma unroll 1
;     for (int sg = 0; sg < SC; sg += 4) {
;       float yy[4];
; #pragma unroll
;       for (int s4 = 0; s4 < 4; ++s4) {
;         const int s = sg + s4;
;         const f32x2* a2 = (const f32x2*)(Al + s * 64 + cg * 8);
;         const f32x2* w2 = (const f32x2*)(Wl + s * 64 + cg * 8);
;         const f32x2* b2 = (const f32x2*)(Bl + s * 64 + cg * 8);
;         const f32x2* k2 = (const f32x2*)(Kl + s * 64 + cg * 8);
;         const f32x2* r2 = (const f32x2*)(Rl + s * 64 + cg * 8);
;         f32x2 o[20];
; #pragma unroll
;         for (int i = 0; i < 4; ++i) { o[i] = a2[i]; o[4 + i] = w2[i]; o[8 + i] = b2[i]; o[12 + i] = k2[i]; o[16 + i] = r2[i]; }
;         const float vr = Vl[s * 64 + 32 * half + rp];
;         f32x2 p0 = St[0] * o[0], p1 = St[1] * o[1];
;         p0 = __builtin_elementwise_fma(St[2], o[2], p0); p1 = __builtin_elementwise_fma(St[3], o[3], p1);
;         const float sa = oct_sum((p0.x + p0.y) + (p1.x + p1.y));
;         const f32x2 sv = {sa, sa}, vv = {vr, vr};
;         f32x2 y0 = {0.f, 0.f}, y1 = {0.f, 0.f};
; #pragma unroll
;         for (int i = 0; i < 4; i += 2) {
;           St[i] = __builtin_elementwise_fma(St[i], o[4 + i], __builtin_elementwise_fma(sv, o[8 + i], vv * o[12 + i]));
;           St[i + 1] = __builtin_elementwise_fma(St[i + 1], o[5 + i], __builtin_elementwise_fma(sv, o[9 + i], vv * o[13 + i]));
;           y0 = __builtin_elementwise_fma(St[i], o[16 + i], y0);
;           y1 = __builtin_elementwise_fma(St[i + 1], o[17 + i], y1);
;         }
;         yy[s4] = oct_sum((y0.x + y0.y) + (y1.x + y1.y));
;       }
;       if (cg == 0) {
; #pragma unroll
;         for (int s4 = 0; s4 < 4; ++s4) Yl[(sg + s4) * 32 + rp] = yy[s4];
;       }
;     }
.LBB0_701:
	s_mov_b32 s26, -4
	v_mov_b32_e32 v0, v214
	v_mov_b32_e32 v161, v160
	v_mov_b32_e32 v162, v225
	ds_read_b128 v[34:37], v0 offset:16384
	ds_read_b128 v[38:41], v0 offset:16400
	ds_read_b128 v[68:71], v0 offset:8192
	ds_read_b128 v[150:153], v0 offset:8208
	ds_read2st64_b32 v[158:159], v161 offset0:0 offset1:1
	ds_read_b128 v[50:53], v0 offset:20480
	ds_read_b128 v[54:57], v0 offset:20496
	ds_read_b128 v[42:45], v0 offset:4096
	ds_read_b128 v[46:49], v0 offset:4112
	ds_read_b128 v[154:157], v0 offset:0
	ds_read_b128 v[246:249], v0 offset:16
	ds_read_b128 v[200:203], v0 offset:16640
	ds_read_b128 v[230:233], v0 offset:16656
	s_waitcnt lgkmcnt(11)
	v_pk_mul_f32 v[34:35], v[66:67], v[34:35]
	v_pk_mul_f32 v[36:37], v[64:65], v[36:37]
	v_pk_fma_f32 v[34:35], v[62:63], v[38:39], v[34:35]
	v_pk_fma_f32 v[36:37], v[60:61], v[40:41], v[36:37]
	s_waitcnt lgkmcnt(8)
	v_pk_mul_f32 v[58:59], v[68:69], v[158:159] op_sel_hi:[1,0]
	v_add_f32_e32 v198, v34, v35
	v_add_f32_e32 v199, v36, v37
	v_pk_mul_f32 v[72:73], v[70:71], v[158:159] op_sel_hi:[1,0]
	v_add_f32_e32 v198, v198, v199
	ds_read_b128 v[68:71], v0 offset:8448
	v_pk_mul_f32 v[212:213], v[150:151], v[158:159] op_sel_hi:[1,0]
	v_add_f32_dpp v198, v198, v198 quad_perm:[1,0,3,2] row_mask:0xf bank_mask:0xf bound_ctrl:1
	s_nop 0
	v_pk_mul_f32 v[250:251], v[152:153], v[158:159] op_sel_hi:[1,0]
	v_add_f32_dpp v198, v198, v198 quad_perm:[2,3,0,1] row_mask:0xf bank_mask:0xf bound_ctrl:1
	s_nop 0
	ds_read_b128 v[150:153], v0 offset:8464
	v_add_f32_dpp v198, v198, v198 row_half_mirror row_mask:0xf bank_mask:0xf bound_ctrl:1
	s_waitcnt lgkmcnt(8)
	v_pk_fma_f32 v[58:59], v[198:199], v[50:51], v[58:59] op_sel_hi:[0,1,1]
	v_pk_fma_f32 v[72:73], v[198:199], v[52:53], v[72:73] op_sel_hi:[0,1,1]
	s_waitcnt lgkmcnt(6)
	v_pk_fma_f32 v[66:67], v[66:67], v[42:43], v[58:59]
	v_pk_fma_f32 v[64:65], v[64:65], v[44:45], v[72:73]
	v_pk_fma_f32 v[212:213], v[198:199], v[54:55], v[212:213] op_sel_hi:[0,1,1]
	v_pk_fma_f32 v[250:251], v[198:199], v[56:57], v[250:251] op_sel_hi:[0,1,1]
	v_pk_fma_f32 v[62:63], v[62:63], v[46:47], v[212:213]
	v_pk_fma_f32 v[60:61], v[60:61], v[48:49], v[250:251]
	ds_read_b128 v[50:53], v0 offset:20736
	ds_read_b128 v[54:57], v0 offset:20752
	ds_read_b128 v[42:45], v0 offset:4352
	ds_read_b128 v[46:49], v0 offset:4368
	s_waitcnt lgkmcnt(8)
	v_pk_fma_f32 v[58:59], v[66:67], v[154:155], 0 op_sel_hi:[1,1,0]
	v_pk_fma_f32 v[72:73], v[64:65], v[156:157], 0 op_sel_hi:[1,1,0]
	v_pk_fma_f32 v[58:59], v[62:63], v[246:247], v[58:59]
	v_pk_fma_f32 v[72:73], v[60:61], v[248:249], v[72:73]
	ds_read_b128 v[154:157], v0 offset:256
	ds_read_b128 v[246:249], v0 offset:272
	v_add_f32_e32 v207, v58, v59
	v_add_f32_e32 v209, v72, v73
	ds_read_b128 v[34:37], v0 offset:16896
	ds_read_b128 v[38:41], v0 offset:16912
	s_waitcnt lgkmcnt(10)
	v_pk_mul_f32 v[200:201], v[66:67], v[200:201]
	v_pk_mul_f32 v[202:203], v[64:65], v[202:203]
	v_pk_fma_f32 v[200:201], v[62:63], v[230:231], v[200:201]
	v_pk_fma_f32 v[202:203], v[60:61], v[232:233], v[202:203]
	v_add_f32_e32 v207, v207, v209
	s_waitcnt lgkmcnt(8)
	v_pk_mul_f32 v[58:59], v[68:69], v[158:159] op_sel:[0,1] op_sel_hi:[1,1]
	v_add_f32_e32 v198, v200, v201
	v_add_f32_e32 v199, v202, v203
	v_pk_mul_f32 v[72:73], v[70:71], v[158:159] op_sel:[0,1] op_sel_hi:[1,1]
	v_add_f32_e32 v198, v198, v199
	ds_read_b128 v[68:71], v0 offset:8704
	v_pk_mul_f32 v[212:213], v[150:151], v[158:159] op_sel:[0,1] op_sel_hi:[1,1]
	v_add_f32_dpp v198, v198, v198 quad_perm:[1,0,3,2] row_mask:0xf bank_mask:0xf bound_ctrl:1
	v_add_f32_dpp v207, v207, v207 quad_perm:[1,0,3,2] row_mask:0xf bank_mask:0xf bound_ctrl:1
	v_pk_mul_f32 v[250:251], v[152:153], v[158:159] op_sel:[0,1] op_sel_hi:[1,1]
	v_add_f32_dpp v198, v198, v198 quad_perm:[2,3,0,1] row_mask:0xf bank_mask:0xf bound_ctrl:1
	v_add_f32_dpp v207, v207, v207 quad_perm:[2,3,0,1] row_mask:0xf bank_mask:0xf bound_ctrl:1
	ds_read_b128 v[150:153], v0 offset:8720
	v_add_f32_dpp v198, v198, v198 row_half_mirror row_mask:0xf bank_mask:0xf bound_ctrl:1
	v_add_f32_dpp v207, v207, v207 row_half_mirror row_mask:0xf bank_mask:0xf bound_ctrl:1
	ds_read2st64_b32 v[158:159], v161 offset0:2 offset1:3
	s_and_saveexec_b64 s[18:19], s[12:13]
	ds_write_b32 v162, v207 offset:0
	s_mov_b64 exec, s[18:19]
	s_waitcnt lgkmcnt(10)
	v_pk_fma_f32 v[58:59], v[198:199], v[50:51], v[58:59] op_sel_hi:[0,1,1]
	v_pk_fma_f32 v[72:73], v[198:199], v[52:53], v[72:73] op_sel_hi:[0,1,1]
	s_waitcnt lgkmcnt(8)
	v_pk_fma_f32 v[66:67], v[66:67], v[42:43], v[58:59]
	v_pk_fma_f32 v[64:65], v[64:65], v[44:45], v[72:73]
	v_pk_fma_f32 v[212:213], v[198:199], v[54:55], v[212:213] op_sel_hi:[0,1,1]
	v_pk_fma_f32 v[250:251], v[198:199], v[56:57], v[250:251] op_sel_hi:[0,1,1]
	v_pk_fma_f32 v[62:63], v[62:63], v[46:47], v[212:213]
	v_pk_fma_f32 v[60:61], v[60:61], v[48:49], v[250:251]
	ds_read_b128 v[50:53], v0 offset:20992
	ds_read_b128 v[54:57], v0 offset:21008
	ds_read_b128 v[42:45], v0 offset:4608
	ds_read_b128 v[46:49], v0 offset:4624
	s_waitcnt lgkmcnt(10)
	v_pk_fma_f32 v[58:59], v[66:67], v[154:155], 0 op_sel_hi:[1,1,0]
	v_pk_fma_f32 v[72:73], v[64:65], v[156:157], 0 op_sel_hi:[1,1,0]
	v_pk_fma_f32 v[58:59], v[62:63], v[246:247], v[58:59]
	v_pk_fma_f32 v[72:73], v[60:61], v[248:249], v[72:73]
	ds_read_b128 v[154:157], v0 offset:512
	ds_read_b128 v[246:249], v0 offset:528
	v_add_f32_e32 v207, v58, v59
	v_add_f32_e32 v209, v72, v73
	ds_read_b128 v[200:203], v0 offset:17152
	ds_read_b128 v[230:233], v0 offset:17168
	s_waitcnt lgkmcnt(12)
	v_pk_mul_f32 v[34:35], v[66:67], v[34:35]
	v_pk_mul_f32 v[36:37], v[64:65], v[36:37]
	v_pk_fma_f32 v[34:35], v[62:63], v[38:39], v[34:35]
	v_pk_fma_f32 v[36:37], v[60:61], v[40:41], v[36:37]
	v_add_f32_e32 v207, v207, v209
	s_waitcnt lgkmcnt(9)
; DI float oct_sum(float v) { v += dpp_f<0xB1>(v); v += dpp_f<0x4E>(v); v += dpp_f<0x141>(v); return v; }
; DI void scan_item(const Params& p, int b, int h, int half, char* smem, unsigned* pgen, unsigned kp) {
;     ...
; #pragma unroll 1
;     for (int sg = 0; sg < SC; sg += 4) {
;       float yy[4];
; #pragma unroll
;       for (int s4 = 0; s4 < 4; ++s4) {
;         const int s = sg + s4;
;         const f32x2* a2 = (const f32x2*)(Al + s * 64 + cg * 8);
;         const f32x2* w2 = (const f32x2*)(Wl + s * 64 + cg * 8);
;         const f32x2* b2 = (const f32x2*)(Bl + s * 64 + cg * 8);
;         const f32x2* k2 = (const f32x2*)(Kl + s * 64 + cg * 8);
;         const f32x2* r2 = (const f32x2*)(Rl + s * 64 + cg * 8);
;         f32x2 o[20];
; #pragma unroll
;         for (int i = 0; i < 4; ++i) { o[i] = a2[i]; o[4 + i] = w2[i]; o[8 + i] = b2[i]; o[12 + i] = k2[i]; o[16 + i] = r2[i]; }
;         const float vr = Vl[s * 64 + 32 * half + rp];
;         f32x2 p0 = St[0] * o[0], p1 = St[1] * o[1];
;         p0 = __builtin_elementwise_fma(St[2], o[2], p0); p1 = __builtin_elementwise_fma(St[3], o[3], p1);
;         const float sa = oct_sum((p0.x + p0.y) + (p1.x + p1.y));
;         const f32x2 sv = {sa, sa}, vv = {vr, vr};
;         f32x2 y0 = {0.f, 0.f}, y1 = {0.f, 0.f};
; #pragma unroll
;         for (int i = 0; i < 4; i += 2) {
;           St[i] = __builtin_elementwise_fma(St[i], o[4 + i], __builtin_elementwise_fma(sv, o[8 + i], vv * o[12 + i]));
;           St[i + 1] = __builtin_elementwise_fma(St[i + 1], o[5 + i], __builtin_elementwise_fma(sv, o[9 + i], vv * o[13 + i]));
;           y0 = __builtin_elementwise_fma(St[i], o[16 + i], y0);
;           y1 = __builtin_elementwise_fma(St[i + 1], o[17 + i], y1);
;         }
;         yy[s4] = oct_sum((y0.x + y0.y) + (y1.x + y1.y));
;       }
;       if (cg == 0) {
; #pragma unroll
;         for (int s4 = 0; s4 < 4; ++s4) Yl[(sg + s4) * 32 + rp] = yy[s4];
;       }
;     }
	v_pk_mul_f32 v[58:59], v[68:69], v[158:159] op_sel_hi:[1,0]
	v_add_f32_e32 v198, v34, v35
	v_add_f32_e32 v199, v36, v37
	v_pk_mul_f32 v[72:73], v[70:71], v[158:159] op_sel_hi:[1,0]
	v_add_f32_e32 v198, v198, v199
	ds_read_b128 v[68:71], v0 offset:8960
	v_pk_mul_f32 v[212:213], v[150:151], v[158:159] op_sel_hi:[1,0]
	v_add_f32_dpp v198, v198, v198 quad_perm:[1,0,3,2] row_mask:0xf bank_mask:0xf bound_ctrl:1
	v_add_f32_dpp v207, v207, v207 quad_perm:[1,0,3,2] row_mask:0xf bank_mask:0xf bound_ctrl:1
	v_pk_mul_f32 v[250:251], v[152:153], v[158:159] op_sel_hi:[1,0]
	v_add_f32_dpp v198, v198, v198 quad_perm:[2,3,0,1] row_mask:0xf bank_mask:0xf bound_ctrl:1
	v_add_f32_dpp v207, v207, v207 quad_perm:[2,3,0,1] row_mask:0xf bank_mask:0xf bound_ctrl:1
	ds_read_b128 v[150:153], v0 offset:8976
	v_add_f32_dpp v198, v198, v198 row_half_mirror row_mask:0xf bank_mask:0xf bound_ctrl:1
	v_add_f32_dpp v207, v207, v207 row_half_mirror row_mask:0xf bank_mask:0xf bound_ctrl:1
	s_and_saveexec_b64 s[18:19], s[12:13]
	ds_write_b32 v162, v207 offset:128
	s_mov_b64 exec, s[18:19]
	s_waitcnt lgkmcnt(9)
	v_pk_fma_f32 v[58:59], v[198:199], v[50:51], v[58:59] op_sel_hi:[0,1,1]
	v_pk_fma_f32 v[72:73], v[198:199], v[52:53], v[72:73] op_sel_hi:[0,1,1]
	s_waitcnt lgkmcnt(7)
	v_pk_fma_f32 v[66:67], v[66:67], v[42:43], v[58:59]
	v_pk_fma_f32 v[64:65], v[64:65], v[44:45], v[72:73]
	v_pk_fma_f32 v[212:213], v[198:199], v[54:55], v[212:213] op_sel_hi:[0,1,1]
	v_pk_fma_f32 v[250:251], v[198:199], v[56:57], v[250:251] op_sel_hi:[0,1,1]
	v_pk_fma_f32 v[62:63], v[62:63], v[46:47], v[212:213]
	v_pk_fma_f32 v[60:61], v[60:61], v[48:49], v[250:251]
	ds_read_b128 v[50:53], v0 offset:21248
	ds_read_b128 v[54:57], v0 offset:21264
	ds_read_b128 v[42:45], v0 offset:4864
	ds_read_b128 v[46:49], v0 offset:4880
	s_waitcnt lgkmcnt(9)
	v_pk_fma_f32 v[58:59], v[66:67], v[154:155], 0 op_sel_hi:[1,1,0]
	v_pk_fma_f32 v[72:73], v[64:65], v[156:157], 0 op_sel_hi:[1,1,0]
	v_pk_fma_f32 v[58:59], v[62:63], v[246:247], v[58:59]
	v_pk_fma_f32 v[72:73], v[60:61], v[248:249], v[72:73]
	ds_read_b128 v[154:157], v0 offset:768
	ds_read_b128 v[246:249], v0 offset:784
	v_add_f32_e32 v207, v58, v59
	v_add_f32_e32 v209, v72, v73
	ds_read_b128 v[34:37], v0 offset:17408
	ds_read_b128 v[38:41], v0 offset:17424
	s_waitcnt lgkmcnt(11)
	v_pk_mul_f32 v[200:201], v[66:67], v[200:201]
	v_pk_mul_f32 v[202:203], v[64:65], v[202:203]
	v_pk_fma_f32 v[200:201], v[62:63], v[230:231], v[200:201]
	v_pk_fma_f32 v[202:203], v[60:61], v[232:233], v[202:203]
	v_add_f32_e32 v207, v207, v209
	s_waitcnt lgkmcnt(9)
	v_pk_mul_f32 v[58:59], v[68:69], v[158:159] op_sel:[0,1] op_sel_hi:[1,1]
	v_add_f32_e32 v198, v200, v201
	v_add_f32_e32 v199, v202, v203
	v_pk_mul_f32 v[72:73], v[70:71], v[158:159] op_sel:[0,1] op_sel_hi:[1,1]
	v_add_f32_e32 v198, v198, v199
	ds_read_b128 v[68:71], v0 offset:9216
	v_pk_mul_f32 v[212:213], v[150:151], v[158:159] op_sel:[0,1] op_sel_hi:[1,1]
	v_add_f32_dpp v198, v198, v198 quad_perm:[1,0,3,2] row_mask:0xf bank_mask:0xf bound_ctrl:1
	v_add_f32_dpp v207, v207, v207 quad_perm:[1,0,3,2] row_mask:0xf bank_mask:0xf bound_ctrl:1
	v_pk_mul_f32 v[250:251], v[152:153], v[158:159] op_sel:[0,1] op_sel_hi:[1,1]
	v_add_f32_dpp v198, v198, v198 quad_perm:[2,3,0,1] row_mask:0xf bank_mask:0xf bound_ctrl:1
	v_add_f32_dpp v207, v207, v207 quad_perm:[2,3,0,1] row_mask:0xf bank_mask:0xf bound_ctrl:1
	ds_read_b128 v[150:153], v0 offset:9232
	v_add_f32_dpp v198, v198, v198 row_half_mirror row_mask:0xf bank_mask:0xf bound_ctrl:1
	v_add_f32_dpp v207, v207, v207 row_half_mirror row_mask:0xf bank_mask:0xf bound_ctrl:1
	ds_read2st64_b32 v[158:159], v161 offset0:4 offset1:5
	s_and_saveexec_b64 s[18:19], s[12:13]
	ds_write_b32 v162, v207 offset:256
	s_mov_b64 exec, s[18:19]
	s_waitcnt lgkmcnt(10)
	v_pk_fma_f32 v[58:59], v[198:199], v[50:51], v[58:59] op_sel_hi:[0,1,1]
	v_pk_fma_f32 v[72:73], v[198:199], v[52:53], v[72:73] op_sel_hi:[0,1,1]
	s_waitcnt lgkmcnt(8)
	v_pk_fma_f32 v[66:67], v[66:67], v[42:43], v[58:59]
	v_pk_fma_f32 v[64:65], v[64:65], v[44:45], v[72:73]
	v_pk_fma_f32 v[212:213], v[198:199], v[54:55], v[212:213] op_sel_hi:[0,1,1]
	v_pk_fma_f32 v[250:251], v[198:199], v[56:57], v[250:251] op_sel_hi:[0,1,1]
	v_pk_fma_f32 v[62:63], v[62:63], v[46:47], v[212:213]
	v_pk_fma_f32 v[60:61], v[60:61], v[48:49], v[250:251]
	ds_read_b128 v[50:53], v0 offset:21504
	ds_read_b128 v[54:57], v0 offset:21520
	ds_read_b128 v[42:45], v0 offset:5120
	ds_read_b128 v[46:49], v0 offset:5136
	s_waitcnt lgkmcnt(10)
	v_pk_fma_f32 v[58:59], v[66:67], v[154:155], 0 op_sel_hi:[1,1,0]
	v_pk_fma_f32 v[72:73], v[64:65], v[156:157], 0 op_sel_hi:[1,1,0]
	v_pk_fma_f32 v[58:59], v[62:63], v[246:247], v[58:59]
	v_pk_fma_f32 v[72:73], v[60:61], v[248:249], v[72:73]
	ds_read_b128 v[154:157], v0 offset:1024
	ds_read_b128 v[246:249], v0 offset:1040
	v_add_f32_e32 v207, v58, v59
	v_add_f32_e32 v209, v72, v73
	ds_read_b128 v[200:203], v0 offset:17664
	ds_read_b128 v[230:233], v0 offset:17680
	s_waitcnt lgkmcnt(12)
	v_pk_mul_f32 v[34:35], v[66:67], v[34:35]
	v_pk_mul_f32 v[36:37], v[64:65], v[36:37]
	v_pk_fma_f32 v[34:35], v[62:63], v[38:39], v[34:35]
	v_pk_fma_f32 v[36:37], v[60:61], v[40:41], v[36:37]
	v_add_f32_e32 v207, v207, v209
	s_waitcnt lgkmcnt(9)
; DI float oct_sum(float v) { v += dpp_f<0xB1>(v); v += dpp_f<0x4E>(v); v += dpp_f<0x141>(v); return v; }
; DI void scan_item(const Params& p, int b, int h, int half, char* smem, unsigned* pgen, unsigned kp) {
;     ...
; #pragma unroll 1
;     for (int sg = 0; sg < SC; sg += 4) {
;       float yy[4];
; #pragma unroll
;       for (int s4 = 0; s4 < 4; ++s4) {
;         const int s = sg + s4;
;         const f32x2* a2 = (const f32x2*)(Al + s * 64 + cg * 8);
;         const f32x2* w2 = (const f32x2*)(Wl + s * 64 + cg * 8);
;         const f32x2* b2 = (const f32x2*)(Bl + s * 64 + cg * 8);
;         const f32x2* k2 = (const f32x2*)(Kl + s * 64 + cg * 8);
;         const f32x2* r2 = (const f32x2*)(Rl + s * 64 + cg * 8);
;         f32x2 o[20];
; #pragma unroll
;         for (int i = 0; i < 4; ++i) { o[i] = a2[i]; o[4 + i] = w2[i]; o[8 + i] = b2[i]; o[12 + i] = k2[i]; o[16 + i] = r2[i]; }
;         const float vr = Vl[s * 64 + 32 * half + rp];
;         f32x2 p0 = St[0] * o[0], p1 = St[1] * o[1];
;         p0 = __builtin_elementwise_fma(St[2], o[2], p0); p1 = __builtin_elementwise_fma(St[3], o[3], p1);
;         const float sa = oct_sum((p0.x + p0.y) + (p1.x + p1.y));
;         const f32x2 sv = {sa, sa}, vv = {vr, vr};
;         f32x2 y0 = {0.f, 0.f}, y1 = {0.f, 0.f};
; #pragma unroll
;         for (int i = 0; i < 4; i += 2) {
;           St[i] = __builtin_elementwise_fma(St[i], o[4 + i], __builtin_elementwise_fma(sv, o[8 + i], vv * o[12 + i]));
;           St[i + 1] = __builtin_elementwise_fma(St[i + 1], o[5 + i], __builtin_elementwise_fma(sv, o[9 + i], vv * o[13 + i]));
;           y0 = __builtin_elementwise_fma(St[i], o[16 + i], y0);
;           y1 = __builtin_elementwise_fma(St[i + 1], o[17 + i], y1);
;         }
;         yy[s4] = oct_sum((y0.x + y0.y) + (y1.x + y1.y));
;       }
;       if (cg == 0) {
; #pragma unroll
;         for (int s4 = 0; s4 < 4; ++s4) Yl[(sg + s4) * 32 + rp] = yy[s4];
;       }
;     }
	v_pk_mul_f32 v[58:59], v[68:69], v[158:159] op_sel_hi:[1,0]
	v_add_f32_e32 v198, v34, v35
	v_add_f32_e32 v199, v36, v37
	v_pk_mul_f32 v[72:73], v[70:71], v[158:159] op_sel_hi:[1,0]
	v_add_f32_e32 v198, v198, v199
	ds_read_b128 v[68:71], v0 offset:9472
	v_pk_mul_f32 v[212:213], v[150:151], v[158:159] op_sel_hi:[1,0]
	v_add_f32_dpp v198, v198, v198 quad_perm:[1,0,3,2] row_mask:0xf bank_mask:0xf bound_ctrl:1
	v_add_f32_dpp v207, v207, v207 quad_perm:[1,0,3,2] row_mask:0xf bank_mask:0xf bound_ctrl:1
	v_pk_mul_f32 v[250:251], v[152:153], v[158:159] op_sel_hi:[1,0]
	v_add_f32_dpp v198, v198, v198 quad_perm:[2,3,0,1] row_mask:0xf bank_mask:0xf bound_ctrl:1
	v_add_f32_dpp v207, v207, v207 quad_perm:[2,3,0,1] row_mask:0xf bank_mask:0xf bound_ctrl:1
	ds_read_b128 v[150:153], v0 offset:9488
	v_add_f32_dpp v198, v198, v198 row_half_mirror row_mask:0xf bank_mask:0xf bound_ctrl:1
	v_add_f32_dpp v207, v207, v207 row_half_mirror row_mask:0xf bank_mask:0xf bound_ctrl:1
	s_and_saveexec_b64 s[18:19], s[12:13]
	ds_write_b32 v162, v207 offset:384
	s_mov_b64 exec, s[18:19]
	s_waitcnt lgkmcnt(9)
	v_pk_fma_f32 v[58:59], v[198:199], v[50:51], v[58:59] op_sel_hi:[0,1,1]
	v_pk_fma_f32 v[72:73], v[198:199], v[52:53], v[72:73] op_sel_hi:[0,1,1]
	s_waitcnt lgkmcnt(7)
	v_pk_fma_f32 v[66:67], v[66:67], v[42:43], v[58:59]
	v_pk_fma_f32 v[64:65], v[64:65], v[44:45], v[72:73]
	v_pk_fma_f32 v[212:213], v[198:199], v[54:55], v[212:213] op_sel_hi:[0,1,1]
	v_pk_fma_f32 v[250:251], v[198:199], v[56:57], v[250:251] op_sel_hi:[0,1,1]
	v_pk_fma_f32 v[62:63], v[62:63], v[46:47], v[212:213]
	v_pk_fma_f32 v[60:61], v[60:61], v[48:49], v[250:251]
	ds_read_b128 v[50:53], v0 offset:21760
	ds_read_b128 v[54:57], v0 offset:21776
	ds_read_b128 v[42:45], v0 offset:5376
	ds_read_b128 v[46:49], v0 offset:5392
	s_waitcnt lgkmcnt(9)
	v_pk_fma_f32 v[58:59], v[66:67], v[154:155], 0 op_sel_hi:[1,1,0]
	v_pk_fma_f32 v[72:73], v[64:65], v[156:157], 0 op_sel_hi:[1,1,0]
	v_pk_fma_f32 v[58:59], v[62:63], v[246:247], v[58:59]
	v_pk_fma_f32 v[72:73], v[60:61], v[248:249], v[72:73]
	ds_read_b128 v[154:157], v0 offset:1280
	ds_read_b128 v[246:249], v0 offset:1296
	v_add_f32_e32 v207, v58, v59
	v_add_f32_e32 v209, v72, v73
	ds_read_b128 v[34:37], v0 offset:17920
	ds_read_b128 v[38:41], v0 offset:17936
	s_waitcnt lgkmcnt(11)
	v_pk_mul_f32 v[200:201], v[66:67], v[200:201]
	v_pk_mul_f32 v[202:203], v[64:65], v[202:203]
	v_pk_fma_f32 v[200:201], v[62:63], v[230:231], v[200:201]
	v_pk_fma_f32 v[202:203], v[60:61], v[232:233], v[202:203]
	v_add_f32_e32 v207, v207, v209
	s_waitcnt lgkmcnt(9)
	v_pk_mul_f32 v[58:59], v[68:69], v[158:159] op_sel:[0,1] op_sel_hi:[1,1]
	v_add_f32_e32 v198, v200, v201
	v_add_f32_e32 v199, v202, v203
	v_pk_mul_f32 v[72:73], v[70:71], v[158:159] op_sel:[0,1] op_sel_hi:[1,1]
	v_add_f32_e32 v198, v198, v199
	ds_read_b128 v[68:71], v0 offset:9728
	v_pk_mul_f32 v[212:213], v[150:151], v[158:159] op_sel:[0,1] op_sel_hi:[1,1]
	v_add_f32_dpp v198, v198, v198 quad_perm:[1,0,3,2] row_mask:0xf bank_mask:0xf bound_ctrl:1
	v_add_f32_dpp v207, v207, v207 quad_perm:[1,0,3,2] row_mask:0xf bank_mask:0xf bound_ctrl:1
	v_pk_mul_f32 v[250:251], v[152:153], v[158:159] op_sel:[0,1] op_sel_hi:[1,1]
	v_add_f32_dpp v198, v198, v198 quad_perm:[2,3,0,1] row_mask:0xf bank_mask:0xf bound_ctrl:1
	v_add_f32_dpp v207, v207, v207 quad_perm:[2,3,0,1] row_mask:0xf bank_mask:0xf bound_ctrl:1
	ds_read_b128 v[150:153], v0 offset:9744
	v_add_f32_dpp v198, v198, v198 row_half_mirror row_mask:0xf bank_mask:0xf bound_ctrl:1
	v_add_f32_dpp v207, v207, v207 row_half_mirror row_mask:0xf bank_mask:0xf bound_ctrl:1
	ds_read2st64_b32 v[158:159], v161 offset0:6 offset1:7
	s_and_saveexec_b64 s[18:19], s[12:13]
	ds_write_b32 v162, v207 offset:512
	s_mov_b64 exec, s[18:19]
	s_waitcnt lgkmcnt(10)
	v_pk_fma_f32 v[58:59], v[198:199], v[50:51], v[58:59] op_sel_hi:[0,1,1]
	v_pk_fma_f32 v[72:73], v[198:199], v[52:53], v[72:73] op_sel_hi:[0,1,1]
	s_waitcnt lgkmcnt(8)
	v_pk_fma_f32 v[66:67], v[66:67], v[42:43], v[58:59]
	v_pk_fma_f32 v[64:65], v[64:65], v[44:45], v[72:73]
	v_pk_fma_f32 v[212:213], v[198:199], v[54:55], v[212:213] op_sel_hi:[0,1,1]
	v_pk_fma_f32 v[250:251], v[198:199], v[56:57], v[250:251] op_sel_hi:[0,1,1]
	v_pk_fma_f32 v[62:63], v[62:63], v[46:47], v[212:213]
	v_pk_fma_f32 v[60:61], v[60:61], v[48:49], v[250:251]
	ds_read_b128 v[50:53], v0 offset:22016
	ds_read_b128 v[54:57], v0 offset:22032
	ds_read_b128 v[42:45], v0 offset:5632
	ds_read_b128 v[46:49], v0 offset:5648
	s_waitcnt lgkmcnt(10)
	v_pk_fma_f32 v[58:59], v[66:67], v[154:155], 0 op_sel_hi:[1,1,0]
	v_pk_fma_f32 v[72:73], v[64:65], v[156:157], 0 op_sel_hi:[1,1,0]
	v_pk_fma_f32 v[58:59], v[62:63], v[246:247], v[58:59]
	v_pk_fma_f32 v[72:73], v[60:61], v[248:249], v[72:73]
	ds_read_b128 v[154:157], v0 offset:1536
	ds_read_b128 v[246:249], v0 offset:1552
	v_add_f32_e32 v207, v58, v59
	v_add_f32_e32 v209, v72, v73
	ds_read_b128 v[200:203], v0 offset:18176
	ds_read_b128 v[230:233], v0 offset:18192
	s_waitcnt lgkmcnt(12)
	v_pk_mul_f32 v[34:35], v[66:67], v[34:35]
	v_pk_mul_f32 v[36:37], v[64:65], v[36:37]
	v_pk_fma_f32 v[34:35], v[62:63], v[38:39], v[34:35]
	v_pk_fma_f32 v[36:37], v[60:61], v[40:41], v[36:37]
	v_add_f32_e32 v207, v207, v209
	s_waitcnt lgkmcnt(9)
; DI float oct_sum(float v) { v += dpp_f<0xB1>(v); v += dpp_f<0x4E>(v); v += dpp_f<0x141>(v); return v; }
; DI void scan_item(const Params& p, int b, int h, int half, char* smem, unsigned* pgen, unsigned kp) {
;     ...
; #pragma unroll 1
;     for (int sg = 0; sg < SC; sg += 4) {
;       float yy[4];
; #pragma unroll
;       for (int s4 = 0; s4 < 4; ++s4) {
;         const int s = sg + s4;
;         const f32x2* a2 = (const f32x2*)(Al + s * 64 + cg * 8);
;         const f32x2* w2 = (const f32x2*)(Wl + s * 64 + cg * 8);
;         const f32x2* b2 = (const f32x2*)(Bl + s * 64 + cg * 8);
;         const f32x2* k2 = (const f32x2*)(Kl + s * 64 + cg * 8);
;         const f32x2* r2 = (const f32x2*)(Rl + s * 64 + cg * 8);
;         f32x2 o[20];
; #pragma unroll
;         for (int i = 0; i < 4; ++i) { o[i] = a2[i]; o[4 + i] = w2[i]; o[8 + i] = b2[i]; o[12 + i] = k2[i]; o[16 + i] = r2[i]; }
;         const float vr = Vl[s * 64 + 32 * half + rp];
;         f32x2 p0 = St[0] * o[0], p1 = St[1] * o[1];
;         p0 = __builtin_elementwise_fma(St[2], o[2], p0); p1 = __builtin_elementwise_fma(St[3], o[3], p1);
;         const float sa = oct_sum((p0.x + p0.y) + (p1.x + p1.y));
;         const f32x2 sv = {sa, sa}, vv = {vr, vr};
;         f32x2 y0 = {0.f, 0.f}, y1 = {0.f, 0.f};
; #pragma unroll
;         for (int i = 0; i < 4; i += 2) {
;           St[i] = __builtin_elementwise_fma(St[i], o[4 + i], __builtin_elementwise_fma(sv, o[8 + i], vv * o[12 + i]));
;           St[i + 1] = __builtin_elementwise_fma(St[i + 1], o[5 + i], __builtin_elementwise_fma(sv, o[9 + i], vv * o[13 + i]));
;           y0 = __builtin_elementwise_fma(St[i], o[16 + i], y0);
;           y1 = __builtin_elementwise_fma(St[i + 1], o[17 + i], y1);
;         }
;         yy[s4] = oct_sum((y0.x + y0.y) + (y1.x + y1.y));
;       }
;       if (cg == 0) {
; #pragma unroll
;         for (int s4 = 0; s4 < 4; ++s4) Yl[(sg + s4) * 32 + rp] = yy[s4];
;       }
;     }
	v_pk_mul_f32 v[58:59], v[68:69], v[158:159] op_sel_hi:[1,0]
	v_add_f32_e32 v198, v34, v35
	v_add_f32_e32 v199, v36, v37
	v_pk_mul_f32 v[72:73], v[70:71], v[158:159] op_sel_hi:[1,0]
	v_add_f32_e32 v198, v198, v199
	ds_read_b128 v[68:71], v0 offset:9984
	v_pk_mul_f32 v[212:213], v[150:151], v[158:159] op_sel_hi:[1,0]
	v_add_f32_dpp v198, v198, v198 quad_perm:[1,0,3,2] row_mask:0xf bank_mask:0xf bound_ctrl:1
	v_add_f32_dpp v207, v207, v207 quad_perm:[1,0,3,2] row_mask:0xf bank_mask:0xf bound_ctrl:1
	v_pk_mul_f32 v[250:251], v[152:153], v[158:159] op_sel_hi:[1,0]
	v_add_f32_dpp v198, v198, v198 quad_perm:[2,3,0,1] row_mask:0xf bank_mask:0xf bound_ctrl:1
	v_add_f32_dpp v207, v207, v207 quad_perm:[2,3,0,1] row_mask:0xf bank_mask:0xf bound_ctrl:1
	ds_read_b128 v[150:153], v0 offset:10000
	v_add_f32_dpp v198, v198, v198 row_half_mirror row_mask:0xf bank_mask:0xf bound_ctrl:1
	v_add_f32_dpp v207, v207, v207 row_half_mirror row_mask:0xf bank_mask:0xf bound_ctrl:1
	s_and_saveexec_b64 s[18:19], s[12:13]
	ds_write_b32 v162, v207 offset:640
	s_mov_b64 exec, s[18:19]
	s_waitcnt lgkmcnt(9)
	v_pk_fma_f32 v[58:59], v[198:199], v[50:51], v[58:59] op_sel_hi:[0,1,1]
	v_pk_fma_f32 v[72:73], v[198:199], v[52:53], v[72:73] op_sel_hi:[0,1,1]
	s_waitcnt lgkmcnt(7)
	v_pk_fma_f32 v[66:67], v[66:67], v[42:43], v[58:59]
	v_pk_fma_f32 v[64:65], v[64:65], v[44:45], v[72:73]
	v_pk_fma_f32 v[212:213], v[198:199], v[54:55], v[212:213] op_sel_hi:[0,1,1]
	v_pk_fma_f32 v[250:251], v[198:199], v[56:57], v[250:251] op_sel_hi:[0,1,1]
	v_pk_fma_f32 v[62:63], v[62:63], v[46:47], v[212:213]
	v_pk_fma_f32 v[60:61], v[60:61], v[48:49], v[250:251]
	ds_read_b128 v[50:53], v0 offset:22272
	ds_read_b128 v[54:57], v0 offset:22288
	ds_read_b128 v[42:45], v0 offset:5888
	ds_read_b128 v[46:49], v0 offset:5904
	s_waitcnt lgkmcnt(9)
	v_pk_fma_f32 v[58:59], v[66:67], v[154:155], 0 op_sel_hi:[1,1,0]
	v_pk_fma_f32 v[72:73], v[64:65], v[156:157], 0 op_sel_hi:[1,1,0]
	v_pk_fma_f32 v[58:59], v[62:63], v[246:247], v[58:59]
	v_pk_fma_f32 v[72:73], v[60:61], v[248:249], v[72:73]
	ds_read_b128 v[154:157], v0 offset:1792
	ds_read_b128 v[246:249], v0 offset:1808
	v_add_f32_e32 v207, v58, v59
	v_add_f32_e32 v209, v72, v73
	ds_read_b128 v[34:37], v0 offset:18432
	ds_read_b128 v[38:41], v0 offset:18448
	s_waitcnt lgkmcnt(11)
	v_pk_mul_f32 v[200:201], v[66:67], v[200:201]
	v_pk_mul_f32 v[202:203], v[64:65], v[202:203]
	v_pk_fma_f32 v[200:201], v[62:63], v[230:231], v[200:201]
	v_pk_fma_f32 v[202:203], v[60:61], v[232:233], v[202:203]
	v_add_f32_e32 v207, v207, v209
	s_waitcnt lgkmcnt(9)
	v_pk_mul_f32 v[58:59], v[68:69], v[158:159] op_sel:[0,1] op_sel_hi:[1,1]
	v_add_f32_e32 v198, v200, v201
	v_add_f32_e32 v199, v202, v203
	v_pk_mul_f32 v[72:73], v[70:71], v[158:159] op_sel:[0,1] op_sel_hi:[1,1]
	v_add_f32_e32 v198, v198, v199
	ds_read_b128 v[68:71], v0 offset:10240
	v_pk_mul_f32 v[212:213], v[150:151], v[158:159] op_sel:[0,1] op_sel_hi:[1,1]
	v_add_f32_dpp v198, v198, v198 quad_perm:[1,0,3,2] row_mask:0xf bank_mask:0xf bound_ctrl:1
	v_add_f32_dpp v207, v207, v207 quad_perm:[1,0,3,2] row_mask:0xf bank_mask:0xf bound_ctrl:1
	v_pk_mul_f32 v[250:251], v[152:153], v[158:159] op_sel:[0,1] op_sel_hi:[1,1]
	v_add_f32_dpp v198, v198, v198 quad_perm:[2,3,0,1] row_mask:0xf bank_mask:0xf bound_ctrl:1
	v_add_f32_dpp v207, v207, v207 quad_perm:[2,3,0,1] row_mask:0xf bank_mask:0xf bound_ctrl:1
	ds_read_b128 v[150:153], v0 offset:10256
	v_add_f32_dpp v198, v198, v198 row_half_mirror row_mask:0xf bank_mask:0xf bound_ctrl:1
	v_add_f32_dpp v207, v207, v207 row_half_mirror row_mask:0xf bank_mask:0xf bound_ctrl:1
	ds_read2st64_b32 v[158:159], v161 offset0:8 offset1:9
	s_and_saveexec_b64 s[18:19], s[12:13]
	ds_write_b32 v162, v207 offset:768
	s_mov_b64 exec, s[18:19]
	s_waitcnt lgkmcnt(10)
	v_pk_fma_f32 v[58:59], v[198:199], v[50:51], v[58:59] op_sel_hi:[0,1,1]
	v_pk_fma_f32 v[72:73], v[198:199], v[52:53], v[72:73] op_sel_hi:[0,1,1]
	s_waitcnt lgkmcnt(8)
	v_pk_fma_f32 v[66:67], v[66:67], v[42:43], v[58:59]
	v_pk_fma_f32 v[64:65], v[64:65], v[44:45], v[72:73]
	v_pk_fma_f32 v[212:213], v[198:199], v[54:55], v[212:213] op_sel_hi:[0,1,1]
	v_pk_fma_f32 v[250:251], v[198:199], v[56:57], v[250:251] op_sel_hi:[0,1,1]
	v_pk_fma_f32 v[62:63], v[62:63], v[46:47], v[212:213]
	v_pk_fma_f32 v[60:61], v[60:61], v[48:49], v[250:251]
	ds_read_b128 v[50:53], v0 offset:22528
	ds_read_b128 v[54:57], v0 offset:22544
	ds_read_b128 v[42:45], v0 offset:6144
	ds_read_b128 v[46:49], v0 offset:6160
	s_waitcnt lgkmcnt(10)
	v_pk_fma_f32 v[58:59], v[66:67], v[154:155], 0 op_sel_hi:[1,1,0]
	v_pk_fma_f32 v[72:73], v[64:65], v[156:157], 0 op_sel_hi:[1,1,0]
	v_pk_fma_f32 v[58:59], v[62:63], v[246:247], v[58:59]
	v_pk_fma_f32 v[72:73], v[60:61], v[248:249], v[72:73]
	ds_read_b128 v[154:157], v0 offset:2048
	ds_read_b128 v[246:249], v0 offset:2064
	v_add_f32_e32 v207, v58, v59
	v_add_f32_e32 v209, v72, v73
	ds_read_b128 v[200:203], v0 offset:18688
	ds_read_b128 v[230:233], v0 offset:18704
	s_waitcnt lgkmcnt(12)
	v_pk_mul_f32 v[34:35], v[66:67], v[34:35]
	v_pk_mul_f32 v[36:37], v[64:65], v[36:37]
	v_pk_fma_f32 v[34:35], v[62:63], v[38:39], v[34:35]
	v_pk_fma_f32 v[36:37], v[60:61], v[40:41], v[36:37]
	v_add_f32_e32 v207, v207, v209
	s_waitcnt lgkmcnt(9)
; DI float oct_sum(float v) { v += dpp_f<0xB1>(v); v += dpp_f<0x4E>(v); v += dpp_f<0x141>(v); return v; }
; DI void scan_item(const Params& p, int b, int h, int half, char* smem, unsigned* pgen, unsigned kp) {
;     ...
; #pragma unroll 1
;     for (int sg = 0; sg < SC; sg += 4) {
;       float yy[4];
; #pragma unroll
;       for (int s4 = 0; s4 < 4; ++s4) {
;         const int s = sg + s4;
;         const f32x2* a2 = (const f32x2*)(Al + s * 64 + cg * 8);
;         const f32x2* w2 = (const f32x2*)(Wl + s * 64 + cg * 8);
;         const f32x2* b2 = (const f32x2*)(Bl + s * 64 + cg * 8);
;         const f32x2* k2 = (const f32x2*)(Kl + s * 64 + cg * 8);
;         const f32x2* r2 = (const f32x2*)(Rl + s * 64 + cg * 8);
;         f32x2 o[20];
; #pragma unroll
;         for (int i = 0; i < 4; ++i) { o[i] = a2[i]; o[4 + i] = w2[i]; o[8 + i] = b2[i]; o[12 + i] = k2[i]; o[16 + i] = r2[i]; }
;         const float vr = Vl[s * 64 + 32 * half + rp];
;         f32x2 p0 = St[0] * o[0], p1 = St[1] * o[1];
;         p0 = __builtin_elementwise_fma(St[2], o[2], p0); p1 = __builtin_elementwise_fma(St[3], o[3], p1);
;         const float sa = oct_sum((p0.x + p0.y) + (p1.x + p1.y));
;         const f32x2 sv = {sa, sa}, vv = {vr, vr};
;         f32x2 y0 = {0.f, 0.f}, y1 = {0.f, 0.f};
; #pragma unroll
;         for (int i = 0; i < 4; i += 2) {
;           St[i] = __builtin_elementwise_fma(St[i], o[4 + i], __builtin_elementwise_fma(sv, o[8 + i], vv * o[12 + i]));
;           St[i + 1] = __builtin_elementwise_fma(St[i + 1], o[5 + i], __builtin_elementwise_fma(sv, o[9 + i], vv * o[13 + i]));
;           y0 = __builtin_elementwise_fma(St[i], o[16 + i], y0);
;           y1 = __builtin_elementwise_fma(St[i + 1], o[17 + i], y1);
;         }
;         yy[s4] = oct_sum((y0.x + y0.y) + (y1.x + y1.y));
;       }
;       if (cg == 0) {
; #pragma unroll
;         for (int s4 = 0; s4 < 4; ++s4) Yl[(sg + s4) * 32 + rp] = yy[s4];
;       }
;     }
	v_pk_mul_f32 v[58:59], v[68:69], v[158:159] op_sel_hi:[1,0]
	v_add_f32_e32 v198, v34, v35
	v_add_f32_e32 v199, v36, v37
	v_pk_mul_f32 v[72:73], v[70:71], v[158:159] op_sel_hi:[1,0]
	v_add_f32_e32 v198, v198, v199
	ds_read_b128 v[68:71], v0 offset:10496
	v_pk_mul_f32 v[212:213], v[150:151], v[158:159] op_sel_hi:[1,0]
	v_add_f32_dpp v198, v198, v198 quad_perm:[1,0,3,2] row_mask:0xf bank_mask:0xf bound_ctrl:1
	v_add_f32_dpp v207, v207, v207 quad_perm:[1,0,3,2] row_mask:0xf bank_mask:0xf bound_ctrl:1
	v_pk_mul_f32 v[250:251], v[152:153], v[158:159] op_sel_hi:[1,0]
	v_add_f32_dpp v198, v198, v198 quad_perm:[2,3,0,1] row_mask:0xf bank_mask:0xf bound_ctrl:1
	v_add_f32_dpp v207, v207, v207 quad_perm:[2,3,0,1] row_mask:0xf bank_mask:0xf bound_ctrl:1
	ds_read_b128 v[150:153], v0 offset:10512
	v_add_f32_dpp v198, v198, v198 row_half_mirror row_mask:0xf bank_mask:0xf bound_ctrl:1
	v_add_f32_dpp v207, v207, v207 row_half_mirror row_mask:0xf bank_mask:0xf bound_ctrl:1
	s_and_saveexec_b64 s[18:19], s[12:13]
	ds_write_b32 v162, v207 offset:896
	s_mov_b64 exec, s[18:19]
	s_waitcnt lgkmcnt(9)
	v_pk_fma_f32 v[58:59], v[198:199], v[50:51], v[58:59] op_sel_hi:[0,1,1]
	v_pk_fma_f32 v[72:73], v[198:199], v[52:53], v[72:73] op_sel_hi:[0,1,1]
	s_waitcnt lgkmcnt(7)
	v_pk_fma_f32 v[66:67], v[66:67], v[42:43], v[58:59]
	v_pk_fma_f32 v[64:65], v[64:65], v[44:45], v[72:73]
	v_pk_fma_f32 v[212:213], v[198:199], v[54:55], v[212:213] op_sel_hi:[0,1,1]
	v_pk_fma_f32 v[250:251], v[198:199], v[56:57], v[250:251] op_sel_hi:[0,1,1]
	v_pk_fma_f32 v[62:63], v[62:63], v[46:47], v[212:213]
	v_pk_fma_f32 v[60:61], v[60:61], v[48:49], v[250:251]
	ds_read_b128 v[50:53], v0 offset:22784
	ds_read_b128 v[54:57], v0 offset:22800
	ds_read_b128 v[42:45], v0 offset:6400
	ds_read_b128 v[46:49], v0 offset:6416
	s_waitcnt lgkmcnt(9)
	v_pk_fma_f32 v[58:59], v[66:67], v[154:155], 0 op_sel_hi:[1,1,0]
	v_pk_fma_f32 v[72:73], v[64:65], v[156:157], 0 op_sel_hi:[1,1,0]
	v_pk_fma_f32 v[58:59], v[62:63], v[246:247], v[58:59]
	v_pk_fma_f32 v[72:73], v[60:61], v[248:249], v[72:73]
	ds_read_b128 v[154:157], v0 offset:2304
	ds_read_b128 v[246:249], v0 offset:2320
	v_add_f32_e32 v207, v58, v59
	v_add_f32_e32 v209, v72, v73
	ds_read_b128 v[34:37], v0 offset:18944
	ds_read_b128 v[38:41], v0 offset:18960
	s_waitcnt lgkmcnt(11)
	v_pk_mul_f32 v[200:201], v[66:67], v[200:201]
	v_pk_mul_f32 v[202:203], v[64:65], v[202:203]
	v_pk_fma_f32 v[200:201], v[62:63], v[230:231], v[200:201]
	v_pk_fma_f32 v[202:203], v[60:61], v[232:233], v[202:203]
	v_add_f32_e32 v207, v207, v209
	s_waitcnt lgkmcnt(9)
	v_pk_mul_f32 v[58:59], v[68:69], v[158:159] op_sel:[0,1] op_sel_hi:[1,1]
	v_add_f32_e32 v198, v200, v201
	v_add_f32_e32 v199, v202, v203
	v_pk_mul_f32 v[72:73], v[70:71], v[158:159] op_sel:[0,1] op_sel_hi:[1,1]
	v_add_f32_e32 v198, v198, v199
	ds_read_b128 v[68:71], v0 offset:10752
	v_pk_mul_f32 v[212:213], v[150:151], v[158:159] op_sel:[0,1] op_sel_hi:[1,1]
	v_add_f32_dpp v198, v198, v198 quad_perm:[1,0,3,2] row_mask:0xf bank_mask:0xf bound_ctrl:1
	v_add_f32_dpp v207, v207, v207 quad_perm:[1,0,3,2] row_mask:0xf bank_mask:0xf bound_ctrl:1
	v_pk_mul_f32 v[250:251], v[152:153], v[158:159] op_sel:[0,1] op_sel_hi:[1,1]
	v_add_f32_dpp v198, v198, v198 quad_perm:[2,3,0,1] row_mask:0xf bank_mask:0xf bound_ctrl:1
	v_add_f32_dpp v207, v207, v207 quad_perm:[2,3,0,1] row_mask:0xf bank_mask:0xf bound_ctrl:1
	ds_read_b128 v[150:153], v0 offset:10768
	v_add_f32_dpp v198, v198, v198 row_half_mirror row_mask:0xf bank_mask:0xf bound_ctrl:1
	v_add_f32_dpp v207, v207, v207 row_half_mirror row_mask:0xf bank_mask:0xf bound_ctrl:1
	ds_read2st64_b32 v[158:159], v161 offset0:10 offset1:11
	s_and_saveexec_b64 s[18:19], s[12:13]
	ds_write_b32 v162, v207 offset:1024
	s_mov_b64 exec, s[18:19]
	s_waitcnt lgkmcnt(10)
	v_pk_fma_f32 v[58:59], v[198:199], v[50:51], v[58:59] op_sel_hi:[0,1,1]
	v_pk_fma_f32 v[72:73], v[198:199], v[52:53], v[72:73] op_sel_hi:[0,1,1]
	s_waitcnt lgkmcnt(8)
	v_pk_fma_f32 v[66:67], v[66:67], v[42:43], v[58:59]
	v_pk_fma_f32 v[64:65], v[64:65], v[44:45], v[72:73]
	v_pk_fma_f32 v[212:213], v[198:199], v[54:55], v[212:213] op_sel_hi:[0,1,1]
	v_pk_fma_f32 v[250:251], v[198:199], v[56:57], v[250:251] op_sel_hi:[0,1,1]
	v_pk_fma_f32 v[62:63], v[62:63], v[46:47], v[212:213]
	v_pk_fma_f32 v[60:61], v[60:61], v[48:49], v[250:251]
	ds_read_b128 v[50:53], v0 offset:23040
	ds_read_b128 v[54:57], v0 offset:23056
	ds_read_b128 v[42:45], v0 offset:6656
	ds_read_b128 v[46:49], v0 offset:6672
	s_waitcnt lgkmcnt(10)
	v_pk_fma_f32 v[58:59], v[66:67], v[154:155], 0 op_sel_hi:[1,1,0]
	v_pk_fma_f32 v[72:73], v[64:65], v[156:157], 0 op_sel_hi:[1,1,0]
	v_pk_fma_f32 v[58:59], v[62:63], v[246:247], v[58:59]
	v_pk_fma_f32 v[72:73], v[60:61], v[248:249], v[72:73]
	ds_read_b128 v[154:157], v0 offset:2560
	ds_read_b128 v[246:249], v0 offset:2576
	v_add_f32_e32 v207, v58, v59
	v_add_f32_e32 v209, v72, v73
	ds_read_b128 v[200:203], v0 offset:19200
	ds_read_b128 v[230:233], v0 offset:19216
	s_waitcnt lgkmcnt(12)
	v_pk_mul_f32 v[34:35], v[66:67], v[34:35]
	v_pk_mul_f32 v[36:37], v[64:65], v[36:37]
	v_pk_fma_f32 v[34:35], v[62:63], v[38:39], v[34:35]
	v_pk_fma_f32 v[36:37], v[60:61], v[40:41], v[36:37]
	v_add_f32_e32 v207, v207, v209
	s_waitcnt lgkmcnt(9)
; DI float oct_sum(float v) { v += dpp_f<0xB1>(v); v += dpp_f<0x4E>(v); v += dpp_f<0x141>(v); return v; }
; DI void scan_item(const Params& p, int b, int h, int half, char* smem, unsigned* pgen, unsigned kp) {
;     ...
; #pragma unroll 1
;     for (int sg = 0; sg < SC; sg += 4) {
;       float yy[4];
; #pragma unroll
;       for (int s4 = 0; s4 < 4; ++s4) {
;         const int s = sg + s4;
;         const f32x2* a2 = (const f32x2*)(Al + s * 64 + cg * 8);
;         const f32x2* w2 = (const f32x2*)(Wl + s * 64 + cg * 8);
;         const f32x2* b2 = (const f32x2*)(Bl + s * 64 + cg * 8);
;         const f32x2* k2 = (const f32x2*)(Kl + s * 64 + cg * 8);
;         const f32x2* r2 = (const f32x2*)(Rl + s * 64 + cg * 8);
;         f32x2 o[20];
; #pragma unroll
;         for (int i = 0; i < 4; ++i) { o[i] = a2[i]; o[4 + i] = w2[i]; o[8 + i] = b2[i]; o[12 + i] = k2[i]; o[16 + i] = r2[i]; }
;         const float vr = Vl[s * 64 + 32 * half + rp];
;         f32x2 p0 = St[0] * o[0], p1 = St[1] * o[1];
;         p0 = __builtin_elementwise_fma(St[2], o[2], p0); p1 = __builtin_elementwise_fma(St[3], o[3], p1);
;         const float sa = oct_sum((p0.x + p0.y) + (p1.x + p1.y));
;         const f32x2 sv = {sa, sa}, vv = {vr, vr};
;         f32x2 y0 = {0.f, 0.f}, y1 = {0.f, 0.f};
; #pragma unroll
;         for (int i = 0; i < 4; i += 2) {
;           St[i] = __builtin_elementwise_fma(St[i], o[4 + i], __builtin_elementwise_fma(sv, o[8 + i], vv * o[12 + i]));
;           St[i + 1] = __builtin_elementwise_fma(St[i + 1], o[5 + i], __builtin_elementwise_fma(sv, o[9 + i], vv * o[13 + i]));
;           y0 = __builtin_elementwise_fma(St[i], o[16 + i], y0);
;           y1 = __builtin_elementwise_fma(St[i + 1], o[17 + i], y1);
;         }
;         yy[s4] = oct_sum((y0.x + y0.y) + (y1.x + y1.y));
;       }
;       if (cg == 0) {
; #pragma unroll
;         for (int s4 = 0; s4 < 4; ++s4) Yl[(sg + s4) * 32 + rp] = yy[s4];
;       }
;     }
	v_pk_mul_f32 v[58:59], v[68:69], v[158:159] op_sel_hi:[1,0]
	v_add_f32_e32 v198, v34, v35
	v_add_f32_e32 v199, v36, v37
	v_pk_mul_f32 v[72:73], v[70:71], v[158:159] op_sel_hi:[1,0]
	v_add_f32_e32 v198, v198, v199
	ds_read_b128 v[68:71], v0 offset:11008
	v_pk_mul_f32 v[212:213], v[150:151], v[158:159] op_sel_hi:[1,0]
	v_add_f32_dpp v198, v198, v198 quad_perm:[1,0,3,2] row_mask:0xf bank_mask:0xf bound_ctrl:1
	v_add_f32_dpp v207, v207, v207 quad_perm:[1,0,3,2] row_mask:0xf bank_mask:0xf bound_ctrl:1
	v_pk_mul_f32 v[250:251], v[152:153], v[158:159] op_sel_hi:[1,0]
	v_add_f32_dpp v198, v198, v198 quad_perm:[2,3,0,1] row_mask:0xf bank_mask:0xf bound_ctrl:1
	v_add_f32_dpp v207, v207, v207 quad_perm:[2,3,0,1] row_mask:0xf bank_mask:0xf bound_ctrl:1
	ds_read_b128 v[150:153], v0 offset:11024
	v_add_f32_dpp v198, v198, v198 row_half_mirror row_mask:0xf bank_mask:0xf bound_ctrl:1
	v_add_f32_dpp v207, v207, v207 row_half_mirror row_mask:0xf bank_mask:0xf bound_ctrl:1
	s_and_saveexec_b64 s[18:19], s[12:13]
	ds_write_b32 v162, v207 offset:1152
	s_mov_b64 exec, s[18:19]
	s_waitcnt lgkmcnt(9)
	v_pk_fma_f32 v[58:59], v[198:199], v[50:51], v[58:59] op_sel_hi:[0,1,1]
	v_pk_fma_f32 v[72:73], v[198:199], v[52:53], v[72:73] op_sel_hi:[0,1,1]
	s_waitcnt lgkmcnt(7)
	v_pk_fma_f32 v[66:67], v[66:67], v[42:43], v[58:59]
	v_pk_fma_f32 v[64:65], v[64:65], v[44:45], v[72:73]
	v_pk_fma_f32 v[212:213], v[198:199], v[54:55], v[212:213] op_sel_hi:[0,1,1]
	v_pk_fma_f32 v[250:251], v[198:199], v[56:57], v[250:251] op_sel_hi:[0,1,1]
	v_pk_fma_f32 v[62:63], v[62:63], v[46:47], v[212:213]
	v_pk_fma_f32 v[60:61], v[60:61], v[48:49], v[250:251]
	ds_read_b128 v[50:53], v0 offset:23296
	ds_read_b128 v[54:57], v0 offset:23312
	ds_read_b128 v[42:45], v0 offset:6912
	ds_read_b128 v[46:49], v0 offset:6928
	s_waitcnt lgkmcnt(9)
	v_pk_fma_f32 v[58:59], v[66:67], v[154:155], 0 op_sel_hi:[1,1,0]
	v_pk_fma_f32 v[72:73], v[64:65], v[156:157], 0 op_sel_hi:[1,1,0]
	v_pk_fma_f32 v[58:59], v[62:63], v[246:247], v[58:59]
	v_pk_fma_f32 v[72:73], v[60:61], v[248:249], v[72:73]
	ds_read_b128 v[154:157], v0 offset:2816
	ds_read_b128 v[246:249], v0 offset:2832
	v_add_f32_e32 v207, v58, v59
	v_add_f32_e32 v209, v72, v73
	ds_read_b128 v[34:37], v0 offset:19456
	ds_read_b128 v[38:41], v0 offset:19472
	s_waitcnt lgkmcnt(11)
	v_pk_mul_f32 v[200:201], v[66:67], v[200:201]
	v_pk_mul_f32 v[202:203], v[64:65], v[202:203]
	v_pk_fma_f32 v[200:201], v[62:63], v[230:231], v[200:201]
	v_pk_fma_f32 v[202:203], v[60:61], v[232:233], v[202:203]
	v_add_f32_e32 v207, v207, v209
	s_waitcnt lgkmcnt(9)
	v_pk_mul_f32 v[58:59], v[68:69], v[158:159] op_sel:[0,1] op_sel_hi:[1,1]
	v_add_f32_e32 v198, v200, v201
	v_add_f32_e32 v199, v202, v203
	v_pk_mul_f32 v[72:73], v[70:71], v[158:159] op_sel:[0,1] op_sel_hi:[1,1]
	v_add_f32_e32 v198, v198, v199
	ds_read_b128 v[68:71], v0 offset:11264
	v_pk_mul_f32 v[212:213], v[150:151], v[158:159] op_sel:[0,1] op_sel_hi:[1,1]
	v_add_f32_dpp v198, v198, v198 quad_perm:[1,0,3,2] row_mask:0xf bank_mask:0xf bound_ctrl:1
	v_add_f32_dpp v207, v207, v207 quad_perm:[1,0,3,2] row_mask:0xf bank_mask:0xf bound_ctrl:1
	v_pk_mul_f32 v[250:251], v[152:153], v[158:159] op_sel:[0,1] op_sel_hi:[1,1]
	v_add_f32_dpp v198, v198, v198 quad_perm:[2,3,0,1] row_mask:0xf bank_mask:0xf bound_ctrl:1
	v_add_f32_dpp v207, v207, v207 quad_perm:[2,3,0,1] row_mask:0xf bank_mask:0xf bound_ctrl:1
	ds_read_b128 v[150:153], v0 offset:11280
	v_add_f32_dpp v198, v198, v198 row_half_mirror row_mask:0xf bank_mask:0xf bound_ctrl:1
	v_add_f32_dpp v207, v207, v207 row_half_mirror row_mask:0xf bank_mask:0xf bound_ctrl:1
	ds_read2st64_b32 v[158:159], v161 offset0:12 offset1:13
	s_and_saveexec_b64 s[18:19], s[12:13]
	ds_write_b32 v162, v207 offset:1280
	s_mov_b64 exec, s[18:19]
	s_waitcnt lgkmcnt(10)
	v_pk_fma_f32 v[58:59], v[198:199], v[50:51], v[58:59] op_sel_hi:[0,1,1]
	v_pk_fma_f32 v[72:73], v[198:199], v[52:53], v[72:73] op_sel_hi:[0,1,1]
	s_waitcnt lgkmcnt(8)
	v_pk_fma_f32 v[66:67], v[66:67], v[42:43], v[58:59]
	v_pk_fma_f32 v[64:65], v[64:65], v[44:45], v[72:73]
	v_pk_fma_f32 v[212:213], v[198:199], v[54:55], v[212:213] op_sel_hi:[0,1,1]
	v_pk_fma_f32 v[250:251], v[198:199], v[56:57], v[250:251] op_sel_hi:[0,1,1]
	v_pk_fma_f32 v[62:63], v[62:63], v[46:47], v[212:213]
	v_pk_fma_f32 v[60:61], v[60:61], v[48:49], v[250:251]
	ds_read_b128 v[50:53], v0 offset:23552
	ds_read_b128 v[54:57], v0 offset:23568
	ds_read_b128 v[42:45], v0 offset:7168
	ds_read_b128 v[46:49], v0 offset:7184
	s_waitcnt lgkmcnt(10)
	v_pk_fma_f32 v[58:59], v[66:67], v[154:155], 0 op_sel_hi:[1,1,0]
	v_pk_fma_f32 v[72:73], v[64:65], v[156:157], 0 op_sel_hi:[1,1,0]
	v_pk_fma_f32 v[58:59], v[62:63], v[246:247], v[58:59]
	v_pk_fma_f32 v[72:73], v[60:61], v[248:249], v[72:73]
	ds_read_b128 v[154:157], v0 offset:3072
	ds_read_b128 v[246:249], v0 offset:3088
	v_add_f32_e32 v207, v58, v59
	v_add_f32_e32 v209, v72, v73
	ds_read_b128 v[200:203], v0 offset:19712
	ds_read_b128 v[230:233], v0 offset:19728
	s_waitcnt lgkmcnt(12)
	v_pk_mul_f32 v[34:35], v[66:67], v[34:35]
	v_pk_mul_f32 v[36:37], v[64:65], v[36:37]
	v_pk_fma_f32 v[34:35], v[62:63], v[38:39], v[34:35]
	v_pk_fma_f32 v[36:37], v[60:61], v[40:41], v[36:37]
	v_add_f32_e32 v207, v207, v209
	s_waitcnt lgkmcnt(9)
; DI float oct_sum(float v) { v += dpp_f<0xB1>(v); v += dpp_f<0x4E>(v); v += dpp_f<0x141>(v); return v; }
; DI void scan_item(const Params& p, int b, int h, int half, char* smem, unsigned* pgen, unsigned kp) {
;     ...
; #pragma unroll 1
;     for (int sg = 0; sg < SC; sg += 4) {
;       float yy[4];
; #pragma unroll
;       for (int s4 = 0; s4 < 4; ++s4) {
;         const int s = sg + s4;
;         const f32x2* a2 = (const f32x2*)(Al + s * 64 + cg * 8);
;         const f32x2* w2 = (const f32x2*)(Wl + s * 64 + cg * 8);
;         const f32x2* b2 = (const f32x2*)(Bl + s * 64 + cg * 8);
;         const f32x2* k2 = (const f32x2*)(Kl + s * 64 + cg * 8);
;         const f32x2* r2 = (const f32x2*)(Rl + s * 64 + cg * 8);
;         f32x2 o[20];
; #pragma unroll
;         for (int i = 0; i < 4; ++i) { o[i] = a2[i]; o[4 + i] = w2[i]; o[8 + i] = b2[i]; o[12 + i] = k2[i]; o[16 + i] = r2[i]; }
;         const float vr = Vl[s * 64 + 32 * half + rp];
;         f32x2 p0 = St[0] * o[0], p1 = St[1] * o[1];
;         p0 = __builtin_elementwise_fma(St[2], o[2], p0); p1 = __builtin_elementwise_fma(St[3], o[3], p1);
;         const float sa = oct_sum((p0.x + p0.y) + (p1.x + p1.y));
;         const f32x2 sv = {sa, sa}, vv = {vr, vr};
;         f32x2 y0 = {0.f, 0.f}, y1 = {0.f, 0.f};
; #pragma unroll
;         for (int i = 0; i < 4; i += 2) {
;           St[i] = __builtin_elementwise_fma(St[i], o[4 + i], __builtin_elementwise_fma(sv, o[8 + i], vv * o[12 + i]));
;           St[i + 1] = __builtin_elementwise_fma(St[i + 1], o[5 + i], __builtin_elementwise_fma(sv, o[9 + i], vv * o[13 + i]));
;           y0 = __builtin_elementwise_fma(St[i], o[16 + i], y0);
;           y1 = __builtin_elementwise_fma(St[i + 1], o[17 + i], y1);
;         }
;         yy[s4] = oct_sum((y0.x + y0.y) + (y1.x + y1.y));
;       }
;       if (cg == 0) {
; #pragma unroll
;         for (int s4 = 0; s4 < 4; ++s4) Yl[(sg + s4) * 32 + rp] = yy[s4];
;       }
;     }
	v_pk_mul_f32 v[58:59], v[68:69], v[158:159] op_sel_hi:[1,0]
	v_add_f32_e32 v198, v34, v35
	v_add_f32_e32 v199, v36, v37
	v_pk_mul_f32 v[72:73], v[70:71], v[158:159] op_sel_hi:[1,0]
	v_add_f32_e32 v198, v198, v199
	ds_read_b128 v[68:71], v0 offset:11520
	v_pk_mul_f32 v[212:213], v[150:151], v[158:159] op_sel_hi:[1,0]
	v_add_f32_dpp v198, v198, v198 quad_perm:[1,0,3,2] row_mask:0xf bank_mask:0xf bound_ctrl:1
	v_add_f32_dpp v207, v207, v207 quad_perm:[1,0,3,2] row_mask:0xf bank_mask:0xf bound_ctrl:1
	v_pk_mul_f32 v[250:251], v[152:153], v[158:159] op_sel_hi:[1,0]
	v_add_f32_dpp v198, v198, v198 quad_perm:[2,3,0,1] row_mask:0xf bank_mask:0xf bound_ctrl:1
	v_add_f32_dpp v207, v207, v207 quad_perm:[2,3,0,1] row_mask:0xf bank_mask:0xf bound_ctrl:1
	ds_read_b128 v[150:153], v0 offset:11536
	v_add_f32_dpp v198, v198, v198 row_half_mirror row_mask:0xf bank_mask:0xf bound_ctrl:1
	v_add_f32_dpp v207, v207, v207 row_half_mirror row_mask:0xf bank_mask:0xf bound_ctrl:1
	s_and_saveexec_b64 s[18:19], s[12:13]
	ds_write_b32 v162, v207 offset:1408
	s_mov_b64 exec, s[18:19]
	s_waitcnt lgkmcnt(9)
	v_pk_fma_f32 v[58:59], v[198:199], v[50:51], v[58:59] op_sel_hi:[0,1,1]
	v_pk_fma_f32 v[72:73], v[198:199], v[52:53], v[72:73] op_sel_hi:[0,1,1]
	s_waitcnt lgkmcnt(7)
	v_pk_fma_f32 v[66:67], v[66:67], v[42:43], v[58:59]
	v_pk_fma_f32 v[64:65], v[64:65], v[44:45], v[72:73]
	v_pk_fma_f32 v[212:213], v[198:199], v[54:55], v[212:213] op_sel_hi:[0,1,1]
	v_pk_fma_f32 v[250:251], v[198:199], v[56:57], v[250:251] op_sel_hi:[0,1,1]
	v_pk_fma_f32 v[62:63], v[62:63], v[46:47], v[212:213]
	v_pk_fma_f32 v[60:61], v[60:61], v[48:49], v[250:251]
	ds_read_b128 v[50:53], v0 offset:23808
	ds_read_b128 v[54:57], v0 offset:23824
	ds_read_b128 v[42:45], v0 offset:7424
	ds_read_b128 v[46:49], v0 offset:7440
	s_waitcnt lgkmcnt(9)
	v_pk_fma_f32 v[58:59], v[66:67], v[154:155], 0 op_sel_hi:[1,1,0]
	v_pk_fma_f32 v[72:73], v[64:65], v[156:157], 0 op_sel_hi:[1,1,0]
	v_pk_fma_f32 v[58:59], v[62:63], v[246:247], v[58:59]
	v_pk_fma_f32 v[72:73], v[60:61], v[248:249], v[72:73]
	ds_read_b128 v[154:157], v0 offset:3328
	ds_read_b128 v[246:249], v0 offset:3344
	v_add_f32_e32 v207, v58, v59
	v_add_f32_e32 v209, v72, v73
	ds_read_b128 v[34:37], v0 offset:19968
	ds_read_b128 v[38:41], v0 offset:19984
	s_waitcnt lgkmcnt(11)
	v_pk_mul_f32 v[200:201], v[66:67], v[200:201]
	v_pk_mul_f32 v[202:203], v[64:65], v[202:203]
	v_pk_fma_f32 v[200:201], v[62:63], v[230:231], v[200:201]
	v_pk_fma_f32 v[202:203], v[60:61], v[232:233], v[202:203]
	v_add_f32_e32 v207, v207, v209
	s_waitcnt lgkmcnt(9)
	v_pk_mul_f32 v[58:59], v[68:69], v[158:159] op_sel:[0,1] op_sel_hi:[1,1]
	v_add_f32_e32 v198, v200, v201
	v_add_f32_e32 v199, v202, v203
	v_pk_mul_f32 v[72:73], v[70:71], v[158:159] op_sel:[0,1] op_sel_hi:[1,1]
	v_add_f32_e32 v198, v198, v199
	ds_read_b128 v[68:71], v0 offset:11776
	v_pk_mul_f32 v[212:213], v[150:151], v[158:159] op_sel:[0,1] op_sel_hi:[1,1]
	v_add_f32_dpp v198, v198, v198 quad_perm:[1,0,3,2] row_mask:0xf bank_mask:0xf bound_ctrl:1
	v_add_f32_dpp v207, v207, v207 quad_perm:[1,0,3,2] row_mask:0xf bank_mask:0xf bound_ctrl:1
	v_pk_mul_f32 v[250:251], v[152:153], v[158:159] op_sel:[0,1] op_sel_hi:[1,1]
	v_add_f32_dpp v198, v198, v198 quad_perm:[2,3,0,1] row_mask:0xf bank_mask:0xf bound_ctrl:1
	v_add_f32_dpp v207, v207, v207 quad_perm:[2,3,0,1] row_mask:0xf bank_mask:0xf bound_ctrl:1
	ds_read_b128 v[150:153], v0 offset:11792
	v_add_f32_dpp v198, v198, v198 row_half_mirror row_mask:0xf bank_mask:0xf bound_ctrl:1
	v_add_f32_dpp v207, v207, v207 row_half_mirror row_mask:0xf bank_mask:0xf bound_ctrl:1
	ds_read2st64_b32 v[158:159], v161 offset0:14 offset1:15
	s_and_saveexec_b64 s[18:19], s[12:13]
	ds_write_b32 v162, v207 offset:1536
	s_mov_b64 exec, s[18:19]
	s_waitcnt lgkmcnt(10)
	v_pk_fma_f32 v[58:59], v[198:199], v[50:51], v[58:59] op_sel_hi:[0,1,1]
	v_pk_fma_f32 v[72:73], v[198:199], v[52:53], v[72:73] op_sel_hi:[0,1,1]
	s_waitcnt lgkmcnt(8)
	v_pk_fma_f32 v[66:67], v[66:67], v[42:43], v[58:59]
	v_pk_fma_f32 v[64:65], v[64:65], v[44:45], v[72:73]
	v_pk_fma_f32 v[212:213], v[198:199], v[54:55], v[212:213] op_sel_hi:[0,1,1]
	v_pk_fma_f32 v[250:251], v[198:199], v[56:57], v[250:251] op_sel_hi:[0,1,1]
	v_pk_fma_f32 v[62:63], v[62:63], v[46:47], v[212:213]
	v_pk_fma_f32 v[60:61], v[60:61], v[48:49], v[250:251]
	ds_read_b128 v[50:53], v0 offset:24064
	ds_read_b128 v[54:57], v0 offset:24080
	ds_read_b128 v[42:45], v0 offset:7680
	ds_read_b128 v[46:49], v0 offset:7696
	s_waitcnt lgkmcnt(10)
	v_pk_fma_f32 v[58:59], v[66:67], v[154:155], 0 op_sel_hi:[1,1,0]
	v_pk_fma_f32 v[72:73], v[64:65], v[156:157], 0 op_sel_hi:[1,1,0]
	v_pk_fma_f32 v[58:59], v[62:63], v[246:247], v[58:59]
	v_pk_fma_f32 v[72:73], v[60:61], v[248:249], v[72:73]
	ds_read_b128 v[154:157], v0 offset:3584
	ds_read_b128 v[246:249], v0 offset:3600
	v_add_f32_e32 v207, v58, v59
	v_add_f32_e32 v209, v72, v73
	ds_read_b128 v[200:203], v0 offset:20224
	ds_read_b128 v[230:233], v0 offset:20240
	s_waitcnt lgkmcnt(12)
; DI float oct_sum(float v) { v += dpp_f<0xB1>(v); v += dpp_f<0x4E>(v); v += dpp_f<0x141>(v); return v; }
; DI void scan_item(const Params& p, int b, int h, int half, char* smem, unsigned* pgen, unsigned kp) {
;     ...
; #pragma unroll 1
;     for (int sg = 0; sg < SC; sg += 4) {
;       float yy[4];
; #pragma unroll
;       for (int s4 = 0; s4 < 4; ++s4) {
;         const int s = sg + s4;
;         const f32x2* a2 = (const f32x2*)(Al + s * 64 + cg * 8);
;         const f32x2* w2 = (const f32x2*)(Wl + s * 64 + cg * 8);
;         const f32x2* b2 = (const f32x2*)(Bl + s * 64 + cg * 8);
;         const f32x2* k2 = (const f32x2*)(Kl + s * 64 + cg * 8);
;         const f32x2* r2 = (const f32x2*)(Rl + s * 64 + cg * 8);
;         f32x2 o[20];
; #pragma unroll
;         for (int i = 0; i < 4; ++i) { o[i] = a2[i]; o[4 + i] = w2[i]; o[8 + i] = b2[i]; o[12 + i] = k2[i]; o[16 + i] = r2[i]; }
;         const float vr = Vl[s * 64 + 32 * half + rp];
;         f32x2 p0 = St[0] * o[0], p1 = St[1] * o[1];
;         p0 = __builtin_elementwise_fma(St[2], o[2], p0); p1 = __builtin_elementwise_fma(St[3], o[3], p1);
;         const float sa = oct_sum((p0.x + p0.y) + (p1.x + p1.y));
;         const f32x2 sv = {sa, sa}, vv = {vr, vr};
;         f32x2 y0 = {0.f, 0.f}, y1 = {0.f, 0.f};
; #pragma unroll
;         for (int i = 0; i < 4; i += 2) {
;           St[i] = __builtin_elementwise_fma(St[i], o[4 + i], __builtin_elementwise_fma(sv, o[8 + i], vv * o[12 + i]));
;           St[i + 1] = __builtin_elementwise_fma(St[i + 1], o[5 + i], __builtin_elementwise_fma(sv, o[9 + i], vv * o[13 + i]));
;           y0 = __builtin_elementwise_fma(St[i], o[16 + i], y0);
;           y1 = __builtin_elementwise_fma(St[i + 1], o[17 + i], y1);
;         }
;         yy[s4] = oct_sum((y0.x + y0.y) + (y1.x + y1.y));
;       }
;       if (cg == 0) {
; #pragma unroll
;         for (int s4 = 0; s4 < 4; ++s4) Yl[(sg + s4) * 32 + rp] = yy[s4];
;       }
;     }
	v_pk_mul_f32 v[34:35], v[66:67], v[34:35]
	v_pk_mul_f32 v[36:37], v[64:65], v[36:37]
	v_pk_fma_f32 v[34:35], v[62:63], v[38:39], v[34:35]
	v_pk_fma_f32 v[36:37], v[60:61], v[40:41], v[36:37]
	v_add_f32_e32 v207, v207, v209
	s_waitcnt lgkmcnt(9)
	v_pk_mul_f32 v[58:59], v[68:69], v[158:159] op_sel_hi:[1,0]
	v_add_f32_e32 v198, v34, v35
	v_add_f32_e32 v199, v36, v37
	v_pk_mul_f32 v[72:73], v[70:71], v[158:159] op_sel_hi:[1,0]
	v_add_f32_e32 v198, v198, v199
	ds_read_b128 v[68:71], v0 offset:12032
	v_pk_mul_f32 v[212:213], v[150:151], v[158:159] op_sel_hi:[1,0]
	v_add_f32_dpp v198, v198, v198 quad_perm:[1,0,3,2] row_mask:0xf bank_mask:0xf bound_ctrl:1
	v_add_f32_dpp v207, v207, v207 quad_perm:[1,0,3,2] row_mask:0xf bank_mask:0xf bound_ctrl:1
	v_pk_mul_f32 v[250:251], v[152:153], v[158:159] op_sel_hi:[1,0]
	v_add_f32_dpp v198, v198, v198 quad_perm:[2,3,0,1] row_mask:0xf bank_mask:0xf bound_ctrl:1
	v_add_f32_dpp v207, v207, v207 quad_perm:[2,3,0,1] row_mask:0xf bank_mask:0xf bound_ctrl:1
	ds_read_b128 v[150:153], v0 offset:12048
	v_add_f32_dpp v198, v198, v198 row_half_mirror row_mask:0xf bank_mask:0xf bound_ctrl:1
	v_add_f32_dpp v207, v207, v207 row_half_mirror row_mask:0xf bank_mask:0xf bound_ctrl:1
	s_and_saveexec_b64 s[18:19], s[12:13]
	ds_write_b32 v162, v207 offset:1664
	s_mov_b64 exec, s[18:19]
	s_waitcnt lgkmcnt(9)
	v_pk_fma_f32 v[58:59], v[198:199], v[50:51], v[58:59] op_sel_hi:[0,1,1]
	v_pk_fma_f32 v[72:73], v[198:199], v[52:53], v[72:73] op_sel_hi:[0,1,1]
	s_waitcnt lgkmcnt(7)
	v_pk_fma_f32 v[66:67], v[66:67], v[42:43], v[58:59]
	v_pk_fma_f32 v[64:65], v[64:65], v[44:45], v[72:73]
	v_pk_fma_f32 v[212:213], v[198:199], v[54:55], v[212:213] op_sel_hi:[0,1,1]
	v_pk_fma_f32 v[250:251], v[198:199], v[56:57], v[250:251] op_sel_hi:[0,1,1]
	v_pk_fma_f32 v[62:63], v[62:63], v[46:47], v[212:213]
	v_pk_fma_f32 v[60:61], v[60:61], v[48:49], v[250:251]
	ds_read_b128 v[50:53], v0 offset:24320
	ds_read_b128 v[54:57], v0 offset:24336
	ds_read_b128 v[42:45], v0 offset:7936
	ds_read_b128 v[46:49], v0 offset:7952
	s_waitcnt lgkmcnt(9)
	v_pk_fma_f32 v[58:59], v[66:67], v[154:155], 0 op_sel_hi:[1,1,0]
	v_pk_fma_f32 v[72:73], v[64:65], v[156:157], 0 op_sel_hi:[1,1,0]
	v_pk_fma_f32 v[58:59], v[62:63], v[246:247], v[58:59]
	v_pk_fma_f32 v[72:73], v[60:61], v[248:249], v[72:73]
	ds_read_b128 v[154:157], v0 offset:3840
	ds_read_b128 v[246:249], v0 offset:3856
	v_add_f32_e32 v207, v58, v59
	v_add_f32_e32 v209, v72, v73
	s_waitcnt lgkmcnt(9)
	v_pk_mul_f32 v[200:201], v[66:67], v[200:201]
	v_pk_mul_f32 v[202:203], v[64:65], v[202:203]
	v_pk_fma_f32 v[200:201], v[62:63], v[230:231], v[200:201]
	v_pk_fma_f32 v[202:203], v[60:61], v[232:233], v[202:203]
	v_add_f32_e32 v207, v207, v209
	s_waitcnt lgkmcnt(7)
	v_pk_mul_f32 v[58:59], v[68:69], v[158:159] op_sel:[0,1] op_sel_hi:[1,1]
	v_add_f32_e32 v198, v200, v201
	v_add_f32_e32 v199, v202, v203
	v_pk_mul_f32 v[72:73], v[70:71], v[158:159] op_sel:[0,1] op_sel_hi:[1,1]
	v_add_f32_e32 v198, v198, v199
	s_nop 0
	v_pk_mul_f32 v[212:213], v[150:151], v[158:159] op_sel:[0,1] op_sel_hi:[1,1]
	v_add_f32_dpp v198, v198, v198 quad_perm:[1,0,3,2] row_mask:0xf bank_mask:0xf bound_ctrl:1
	v_add_f32_dpp v207, v207, v207 quad_perm:[1,0,3,2] row_mask:0xf bank_mask:0xf bound_ctrl:1
	v_pk_mul_f32 v[250:251], v[152:153], v[158:159] op_sel:[0,1] op_sel_hi:[1,1]
	v_add_f32_dpp v198, v198, v198 quad_perm:[2,3,0,1] row_mask:0xf bank_mask:0xf bound_ctrl:1
	v_add_f32_dpp v207, v207, v207 quad_perm:[2,3,0,1] row_mask:0xf bank_mask:0xf bound_ctrl:1
	s_nop 0
	v_add_f32_dpp v198, v198, v198 row_half_mirror row_mask:0xf bank_mask:0xf bound_ctrl:1
	v_add_f32_dpp v207, v207, v207 row_half_mirror row_mask:0xf bank_mask:0xf bound_ctrl:1
	s_and_saveexec_b64 s[18:19], s[12:13]
	ds_write_b32 v162, v207 offset:1792
	s_mov_b64 exec, s[18:19]
	s_waitcnt lgkmcnt(5)
	v_pk_fma_f32 v[58:59], v[198:199], v[50:51], v[58:59] op_sel_hi:[0,1,1]
	v_pk_fma_f32 v[72:73], v[198:199], v[52:53], v[72:73] op_sel_hi:[0,1,1]
	s_waitcnt lgkmcnt(3)
	v_pk_fma_f32 v[66:67], v[66:67], v[42:43], v[58:59]
	v_pk_fma_f32 v[64:65], v[64:65], v[44:45], v[72:73]
	v_pk_fma_f32 v[212:213], v[198:199], v[54:55], v[212:213] op_sel_hi:[0,1,1]
	v_pk_fma_f32 v[250:251], v[198:199], v[56:57], v[250:251] op_sel_hi:[0,1,1]
	v_pk_fma_f32 v[62:63], v[62:63], v[46:47], v[212:213]
	v_pk_fma_f32 v[60:61], v[60:61], v[48:49], v[250:251]
	s_waitcnt lgkmcnt(1)
	v_pk_fma_f32 v[58:59], v[66:67], v[154:155], 0 op_sel_hi:[1,1,0]
	v_pk_fma_f32 v[72:73], v[64:65], v[156:157], 0 op_sel_hi:[1,1,0]
	v_pk_fma_f32 v[58:59], v[62:63], v[246:247], v[58:59]
	v_pk_fma_f32 v[72:73], v[60:61], v[248:249], v[72:73]
	v_add_f32_e32 v207, v58, v59
	v_add_f32_e32 v209, v72, v73
	v_add_f32_e32 v207, v207, v209
	s_nop 1
	v_add_f32_dpp v207, v207, v207 quad_perm:[1,0,3,2] row_mask:0xf bank_mask:0xf bound_ctrl:1
	s_nop 1
	v_add_f32_dpp v207, v207, v207 quad_perm:[2,3,0,1] row_mask:0xf bank_mask:0xf bound_ctrl:1
	s_nop 1
	v_add_f32_dpp v207, v207, v207 row_half_mirror row_mask:0xf bank_mask:0xf bound_ctrl:1
	s_and_saveexec_b64 s[18:19], s[12:13]
	ds_write_b32 v162, v207 offset:1920
	s_mov_b64 exec, s[18:19]

; DI float oct_sum(float v) { v += dpp_f<0xB1>(v); v += dpp_f<0x4E>(v); v += dpp_f<0x141>(v); return v; }
; DI void scan_item(const Params& p, int b, int h, int half, char* smem, unsigned* pgen, unsigned kp) {
;     ...
; #pragma unroll 1
;     for (int sg = 0; sg < SC; sg += 4) {
;       float yy[4];
; #pragma unroll
;       for (int s4 = 0; s4 < 4; ++s4) {
;         const int s = sg + s4;
;         const f32x2* a2 = (const f32x2*)(Al + s * 64 + cg * 8);
;         const f32x2* w2 = (const f32x2*)(Wl + s * 64 + cg * 8);
;         const f32x2* b2 = (const f32x2*)(Bl + s * 64 + cg * 8);
;         const f32x2* k2 = (const f32x2*)(Kl + s * 64 + cg * 8);
;         const f32x2* r2 = (const f32x2*)(Rl + s * 64 + cg * 8);
;         f32x2 o[20];
; #pragma unroll
;         for (int i = 0; i < 4; ++i) { o[i] = a2[i]; o[4 + i] = w2[i]; o[8 + i] = b2[i]; o[12 + i] = k2[i]; o[16 + i] = r2[i]; }
;         const float vr = Vl[s * 64 + 32 * half + rp];
;         f32x2 p0 = St[0] * o[0], p1 = St[1] * o[1];
;         p0 = __builtin_elementwise_fma(St[2], o[2], p0); p1 = __builtin_elementwise_fma(St[3], o[3], p1);
;         const float sa = oct_sum((p0.x + p0.y) + (p1.x + p1.y));
;         const f32x2 sv = {sa, sa}, vv = {vr, vr};
;         f32x2 y0 = {0.f, 0.f}, y1 = {0.f, 0.f};
; #pragma unroll
;         for (int i = 0; i < 4; i += 2) {
;           St[i] = __builtin_elementwise_fma(St[i], o[4 + i], __builtin_elementwise_fma(sv, o[8 + i], vv * o[12 + i]));
;           St[i + 1] = __builtin_elementwise_fma(St[i + 1], o[5 + i], __builtin_elementwise_fma(sv, o[9 + i], vv * o[13 + i]));
;           y0 = __builtin_elementwise_fma(St[i], o[16 + i], y0);
;           y1 = __builtin_elementwise_fma(St[i + 1], o[17 + i], y1);
;         }
;         yy[s4] = oct_sum((y0.x + y0.y) + (y1.x + y1.y));
;       }
;       if (cg == 0) {
; #pragma unroll
;         for (int s4 = 0; s4 < 4; ++s4) Yl[(sg + s4) * 32 + rp] = yy[s4];
;       }
;     }
.LBB0_711:
	s_mov_b32 s18, -4
	v_mov_b32_e32 v0, v214
	v_mov_b32_e32 v161, v160
	v_mov_b32_e32 v162, v225
	ds_read_b128 v[34:37], v0 offset:16384
	ds_read_b128 v[38:41], v0 offset:16400
	ds_read_b128 v[68:71], v0 offset:8192
	ds_read_b128 v[150:153], v0 offset:8208
	ds_read2st64_b32 v[158:159], v161 offset0:0 offset1:1
	ds_read_b128 v[50:53], v0 offset:20480
	ds_read_b128 v[54:57], v0 offset:20496
	ds_read_b128 v[42:45], v0 offset:4096
	ds_read_b128 v[46:49], v0 offset:4112
	ds_read_b128 v[154:157], v0 offset:0
	ds_read_b128 v[246:249], v0 offset:16
	ds_read_b128 v[200:203], v0 offset:16640
	ds_read_b128 v[230:233], v0 offset:16656
	s_waitcnt lgkmcnt(11)
	v_pk_mul_f32 v[34:35], v[66:67], v[34:35]
	v_pk_mul_f32 v[36:37], v[64:65], v[36:37]
	v_pk_fma_f32 v[34:35], v[62:63], v[38:39], v[34:35]
	v_pk_fma_f32 v[36:37], v[60:61], v[40:41], v[36:37]
	s_waitcnt lgkmcnt(8)
	v_pk_mul_f32 v[58:59], v[68:69], v[158:159] op_sel_hi:[1,0]
	v_add_f32_e32 v198, v34, v35
	v_add_f32_e32 v199, v36, v37
	v_pk_mul_f32 v[72:73], v[70:71], v[158:159] op_sel_hi:[1,0]
	v_add_f32_e32 v198, v198, v199
	ds_read_b128 v[68:71], v0 offset:8448
	v_pk_mul_f32 v[212:213], v[150:151], v[158:159] op_sel_hi:[1,0]
	v_add_f32_dpp v198, v198, v198 quad_perm:[1,0,3,2] row_mask:0xf bank_mask:0xf bound_ctrl:1
	s_nop 0
	v_pk_mul_f32 v[250:251], v[152:153], v[158:159] op_sel_hi:[1,0]
	v_add_f32_dpp v198, v198, v198 quad_perm:[2,3,0,1] row_mask:0xf bank_mask:0xf bound_ctrl:1
	s_nop 0
	ds_read_b128 v[150:153], v0 offset:8464
	v_add_f32_dpp v198, v198, v198 row_half_mirror row_mask:0xf bank_mask:0xf bound_ctrl:1
	s_waitcnt lgkmcnt(8)
	v_pk_fma_f32 v[58:59], v[198:199], v[50:51], v[58:59] op_sel_hi:[0,1,1]
	v_pk_fma_f32 v[72:73], v[198:199], v[52:53], v[72:73] op_sel_hi:[0,1,1]
	s_waitcnt lgkmcnt(6)
	v_pk_fma_f32 v[66:67], v[66:67], v[42:43], v[58:59]
	v_pk_fma_f32 v[64:65], v[64:65], v[44:45], v[72:73]
	v_pk_fma_f32 v[212:213], v[198:199], v[54:55], v[212:213] op_sel_hi:[0,1,1]
	v_pk_fma_f32 v[250:251], v[198:199], v[56:57], v[250:251] op_sel_hi:[0,1,1]
	v_pk_fma_f32 v[62:63], v[62:63], v[46:47], v[212:213]
	v_pk_fma_f32 v[60:61], v[60:61], v[48:49], v[250:251]
	ds_read_b128 v[50:53], v0 offset:20736
	ds_read_b128 v[54:57], v0 offset:20752
	ds_read_b128 v[42:45], v0 offset:4352
	ds_read_b128 v[46:49], v0 offset:4368
	s_waitcnt lgkmcnt(8)
	v_pk_fma_f32 v[58:59], v[66:67], v[154:155], 0 op_sel_hi:[1,1,0]
	v_pk_fma_f32 v[72:73], v[64:65], v[156:157], 0 op_sel_hi:[1,1,0]
	v_pk_fma_f32 v[58:59], v[62:63], v[246:247], v[58:59]
	v_pk_fma_f32 v[72:73], v[60:61], v[248:249], v[72:73]
	ds_read_b128 v[154:157], v0 offset:256
	ds_read_b128 v[246:249], v0 offset:272
	v_add_f32_e32 v207, v58, v59
	v_add_f32_e32 v209, v72, v73
	ds_read_b128 v[34:37], v0 offset:16896
	ds_read_b128 v[38:41], v0 offset:16912
	s_waitcnt lgkmcnt(10)
	v_pk_mul_f32 v[200:201], v[66:67], v[200:201]
	v_pk_mul_f32 v[202:203], v[64:65], v[202:203]
	v_pk_fma_f32 v[200:201], v[62:63], v[230:231], v[200:201]
	v_pk_fma_f32 v[202:203], v[60:61], v[232:233], v[202:203]
	v_add_f32_e32 v207, v207, v209
	s_waitcnt lgkmcnt(8)
	v_pk_mul_f32 v[58:59], v[68:69], v[158:159] op_sel:[0,1] op_sel_hi:[1,1]
	v_add_f32_e32 v198, v200, v201
	v_add_f32_e32 v199, v202, v203
	v_pk_mul_f32 v[72:73], v[70:71], v[158:159] op_sel:[0,1] op_sel_hi:[1,1]
	v_add_f32_e32 v198, v198, v199
	ds_read_b128 v[68:71], v0 offset:8704
	v_pk_mul_f32 v[212:213], v[150:151], v[158:159] op_sel:[0,1] op_sel_hi:[1,1]
	v_add_f32_dpp v198, v198, v198 quad_perm:[1,0,3,2] row_mask:0xf bank_mask:0xf bound_ctrl:1
	v_add_f32_dpp v207, v207, v207 quad_perm:[1,0,3,2] row_mask:0xf bank_mask:0xf bound_ctrl:1
	v_pk_mul_f32 v[250:251], v[152:153], v[158:159] op_sel:[0,1] op_sel_hi:[1,1]
	v_add_f32_dpp v198, v198, v198 quad_perm:[2,3,0,1] row_mask:0xf bank_mask:0xf bound_ctrl:1
	v_add_f32_dpp v207, v207, v207 quad_perm:[2,3,0,1] row_mask:0xf bank_mask:0xf bound_ctrl:1
	ds_read_b128 v[150:153], v0 offset:8720
	v_add_f32_dpp v198, v198, v198 row_half_mirror row_mask:0xf bank_mask:0xf bound_ctrl:1
	v_add_f32_dpp v207, v207, v207 row_half_mirror row_mask:0xf bank_mask:0xf bound_ctrl:1
	ds_read2st64_b32 v[158:159], v161 offset0:2 offset1:3
	s_and_saveexec_b64 s[4:5], s[12:13]
	ds_write_b32 v162, v207 offset:0
	s_mov_b64 exec, s[4:5]
	s_waitcnt lgkmcnt(10)
	v_pk_fma_f32 v[58:59], v[198:199], v[50:51], v[58:59] op_sel_hi:[0,1,1]
	v_pk_fma_f32 v[72:73], v[198:199], v[52:53], v[72:73] op_sel_hi:[0,1,1]
	s_waitcnt lgkmcnt(8)
	v_pk_fma_f32 v[66:67], v[66:67], v[42:43], v[58:59]
	v_pk_fma_f32 v[64:65], v[64:65], v[44:45], v[72:73]
	v_pk_fma_f32 v[212:213], v[198:199], v[54:55], v[212:213] op_sel_hi:[0,1,1]
	v_pk_fma_f32 v[250:251], v[198:199], v[56:57], v[250:251] op_sel_hi:[0,1,1]
	v_pk_fma_f32 v[62:63], v[62:63], v[46:47], v[212:213]
	v_pk_fma_f32 v[60:61], v[60:61], v[48:49], v[250:251]
	ds_read_b128 v[50:53], v0 offset:20992
	ds_read_b128 v[54:57], v0 offset:21008
	ds_read_b128 v[42:45], v0 offset:4608
	ds_read_b128 v[46:49], v0 offset:4624
	s_waitcnt lgkmcnt(10)
	v_pk_fma_f32 v[58:59], v[66:67], v[154:155], 0 op_sel_hi:[1,1,0]
	v_pk_fma_f32 v[72:73], v[64:65], v[156:157], 0 op_sel_hi:[1,1,0]
	v_pk_fma_f32 v[58:59], v[62:63], v[246:247], v[58:59]
	v_pk_fma_f32 v[72:73], v[60:61], v[248:249], v[72:73]
	ds_read_b128 v[154:157], v0 offset:512
	ds_read_b128 v[246:249], v0 offset:528
	v_add_f32_e32 v207, v58, v59
	v_add_f32_e32 v209, v72, v73
	ds_read_b128 v[200:203], v0 offset:17152
	ds_read_b128 v[230:233], v0 offset:17168
	s_waitcnt lgkmcnt(12)
	v_pk_mul_f32 v[34:35], v[66:67], v[34:35]
	v_pk_mul_f32 v[36:37], v[64:65], v[36:37]
	v_pk_fma_f32 v[34:35], v[62:63], v[38:39], v[34:35]
	v_pk_fma_f32 v[36:37], v[60:61], v[40:41], v[36:37]
	v_add_f32_e32 v207, v207, v209
	s_waitcnt lgkmcnt(9)
; DI float oct_sum(float v) { v += dpp_f<0xB1>(v); v += dpp_f<0x4E>(v); v += dpp_f<0x141>(v); return v; }
; DI void scan_item(const Params& p, int b, int h, int half, char* smem, unsigned* pgen, unsigned kp) {
;     ...
; #pragma unroll 1
;     for (int sg = 0; sg < SC; sg += 4) {
;       float yy[4];
; #pragma unroll
;       for (int s4 = 0; s4 < 4; ++s4) {
;         const int s = sg + s4;
;         const f32x2* a2 = (const f32x2*)(Al + s * 64 + cg * 8);
;         const f32x2* w2 = (const f32x2*)(Wl + s * 64 + cg * 8);
;         const f32x2* b2 = (const f32x2*)(Bl + s * 64 + cg * 8);
;         const f32x2* k2 = (const f32x2*)(Kl + s * 64 + cg * 8);
;         const f32x2* r2 = (const f32x2*)(Rl + s * 64 + cg * 8);
;         f32x2 o[20];
; #pragma unroll
;         for (int i = 0; i < 4; ++i) { o[i] = a2[i]; o[4 + i] = w2[i]; o[8 + i] = b2[i]; o[12 + i] = k2[i]; o[16 + i] = r2[i]; }
;         const float vr = Vl[s * 64 + 32 * half + rp];
;         f32x2 p0 = St[0] * o[0], p1 = St[1] * o[1];
;         p0 = __builtin_elementwise_fma(St[2], o[2], p0); p1 = __builtin_elementwise_fma(St[3], o[3], p1);
;         const float sa = oct_sum((p0.x + p0.y) + (p1.x + p1.y));
;         const f32x2 sv = {sa, sa}, vv = {vr, vr};
;         f32x2 y0 = {0.f, 0.f}, y1 = {0.f, 0.f};
; #pragma unroll
;         for (int i = 0; i < 4; i += 2) {
;           St[i] = __builtin_elementwise_fma(St[i], o[4 + i], __builtin_elementwise_fma(sv, o[8 + i], vv * o[12 + i]));
;           St[i + 1] = __builtin_elementwise_fma(St[i + 1], o[5 + i], __builtin_elementwise_fma(sv, o[9 + i], vv * o[13 + i]));
;           y0 = __builtin_elementwise_fma(St[i], o[16 + i], y0);
;           y1 = __builtin_elementwise_fma(St[i + 1], o[17 + i], y1);
;         }
;         yy[s4] = oct_sum((y0.x + y0.y) + (y1.x + y1.y));
;       }
;       if (cg == 0) {
; #pragma unroll
;         for (int s4 = 0; s4 < 4; ++s4) Yl[(sg + s4) * 32 + rp] = yy[s4];
;       }
;     }
	v_pk_mul_f32 v[58:59], v[68:69], v[158:159] op_sel_hi:[1,0]
	v_add_f32_e32 v198, v34, v35
	v_add_f32_e32 v199, v36, v37
	v_pk_mul_f32 v[72:73], v[70:71], v[158:159] op_sel_hi:[1,0]
	v_add_f32_e32 v198, v198, v199
	ds_read_b128 v[68:71], v0 offset:8960
	v_pk_mul_f32 v[212:213], v[150:151], v[158:159] op_sel_hi:[1,0]
	v_add_f32_dpp v198, v198, v198 quad_perm:[1,0,3,2] row_mask:0xf bank_mask:0xf bound_ctrl:1
	v_add_f32_dpp v207, v207, v207 quad_perm:[1,0,3,2] row_mask:0xf bank_mask:0xf bound_ctrl:1
	v_pk_mul_f32 v[250:251], v[152:153], v[158:159] op_sel_hi:[1,0]
	v_add_f32_dpp v198, v198, v198 quad_perm:[2,3,0,1] row_mask:0xf bank_mask:0xf bound_ctrl:1
	v_add_f32_dpp v207, v207, v207 quad_perm:[2,3,0,1] row_mask:0xf bank_mask:0xf bound_ctrl:1
	ds_read_b128 v[150:153], v0 offset:8976
	v_add_f32_dpp v198, v198, v198 row_half_mirror row_mask:0xf bank_mask:0xf bound_ctrl:1
	v_add_f32_dpp v207, v207, v207 row_half_mirror row_mask:0xf bank_mask:0xf bound_ctrl:1
	s_and_saveexec_b64 s[4:5], s[12:13]
	ds_write_b32 v162, v207 offset:128
	s_mov_b64 exec, s[4:5]
	s_waitcnt lgkmcnt(9)
	v_pk_fma_f32 v[58:59], v[198:199], v[50:51], v[58:59] op_sel_hi:[0,1,1]
	v_pk_fma_f32 v[72:73], v[198:199], v[52:53], v[72:73] op_sel_hi:[0,1,1]
	s_waitcnt lgkmcnt(7)
	v_pk_fma_f32 v[66:67], v[66:67], v[42:43], v[58:59]
	v_pk_fma_f32 v[64:65], v[64:65], v[44:45], v[72:73]
	v_pk_fma_f32 v[212:213], v[198:199], v[54:55], v[212:213] op_sel_hi:[0,1,1]
	v_pk_fma_f32 v[250:251], v[198:199], v[56:57], v[250:251] op_sel_hi:[0,1,1]
	v_pk_fma_f32 v[62:63], v[62:63], v[46:47], v[212:213]
	v_pk_fma_f32 v[60:61], v[60:61], v[48:49], v[250:251]
	ds_read_b128 v[50:53], v0 offset:21248
	ds_read_b128 v[54:57], v0 offset:21264
	ds_read_b128 v[42:45], v0 offset:4864
	ds_read_b128 v[46:49], v0 offset:4880
	s_waitcnt lgkmcnt(9)
	v_pk_fma_f32 v[58:59], v[66:67], v[154:155], 0 op_sel_hi:[1,1,0]
	v_pk_fma_f32 v[72:73], v[64:65], v[156:157], 0 op_sel_hi:[1,1,0]
	v_pk_fma_f32 v[58:59], v[62:63], v[246:247], v[58:59]
	v_pk_fma_f32 v[72:73], v[60:61], v[248:249], v[72:73]
	ds_read_b128 v[154:157], v0 offset:768
	ds_read_b128 v[246:249], v0 offset:784
	v_add_f32_e32 v207, v58, v59
	v_add_f32_e32 v209, v72, v73
	ds_read_b128 v[34:37], v0 offset:17408
	ds_read_b128 v[38:41], v0 offset:17424
	s_waitcnt lgkmcnt(11)
	v_pk_mul_f32 v[200:201], v[66:67], v[200:201]
	v_pk_mul_f32 v[202:203], v[64:65], v[202:203]
	v_pk_fma_f32 v[200:201], v[62:63], v[230:231], v[200:201]
	v_pk_fma_f32 v[202:203], v[60:61], v[232:233], v[202:203]
	v_add_f32_e32 v207, v207, v209
	s_waitcnt lgkmcnt(9)
	v_pk_mul_f32 v[58:59], v[68:69], v[158:159] op_sel:[0,1] op_sel_hi:[1,1]
	v_add_f32_e32 v198, v200, v201
	v_add_f32_e32 v199, v202, v203
	v_pk_mul_f32 v[72:73], v[70:71], v[158:159] op_sel:[0,1] op_sel_hi:[1,1]
	v_add_f32_e32 v198, v198, v199
	ds_read_b128 v[68:71], v0 offset:9216
	v_pk_mul_f32 v[212:213], v[150:151], v[158:159] op_sel:[0,1] op_sel_hi:[1,1]
	v_add_f32_dpp v198, v198, v198 quad_perm:[1,0,3,2] row_mask:0xf bank_mask:0xf bound_ctrl:1
	v_add_f32_dpp v207, v207, v207 quad_perm:[1,0,3,2] row_mask:0xf bank_mask:0xf bound_ctrl:1
	v_pk_mul_f32 v[250:251], v[152:153], v[158:159] op_sel:[0,1] op_sel_hi:[1,1]
	v_add_f32_dpp v198, v198, v198 quad_perm:[2,3,0,1] row_mask:0xf bank_mask:0xf bound_ctrl:1
	v_add_f32_dpp v207, v207, v207 quad_perm:[2,3,0,1] row_mask:0xf bank_mask:0xf bound_ctrl:1
	ds_read_b128 v[150:153], v0 offset:9232
	v_add_f32_dpp v198, v198, v198 row_half_mirror row_mask:0xf bank_mask:0xf bound_ctrl:1
	v_add_f32_dpp v207, v207, v207 row_half_mirror row_mask:0xf bank_mask:0xf bound_ctrl:1
	ds_read2st64_b32 v[158:159], v161 offset0:4 offset1:5
	s_and_saveexec_b64 s[4:5], s[12:13]
	ds_write_b32 v162, v207 offset:256
	s_mov_b64 exec, s[4:5]
	s_waitcnt lgkmcnt(10)
	v_pk_fma_f32 v[58:59], v[198:199], v[50:51], v[58:59] op_sel_hi:[0,1,1]
	v_pk_fma_f32 v[72:73], v[198:199], v[52:53], v[72:73] op_sel_hi:[0,1,1]
	s_waitcnt lgkmcnt(8)
	v_pk_fma_f32 v[66:67], v[66:67], v[42:43], v[58:59]
	v_pk_fma_f32 v[64:65], v[64:65], v[44:45], v[72:73]
	v_pk_fma_f32 v[212:213], v[198:199], v[54:55], v[212:213] op_sel_hi:[0,1,1]
	v_pk_fma_f32 v[250:251], v[198:199], v[56:57], v[250:251] op_sel_hi:[0,1,1]
	v_pk_fma_f32 v[62:63], v[62:63], v[46:47], v[212:213]
	v_pk_fma_f32 v[60:61], v[60:61], v[48:49], v[250:251]
	ds_read_b128 v[50:53], v0 offset:21504
	ds_read_b128 v[54:57], v0 offset:21520
	ds_read_b128 v[42:45], v0 offset:5120
	ds_read_b128 v[46:49], v0 offset:5136
	s_waitcnt lgkmcnt(10)
	v_pk_fma_f32 v[58:59], v[66:67], v[154:155], 0 op_sel_hi:[1,1,0]
	v_pk_fma_f32 v[72:73], v[64:65], v[156:157], 0 op_sel_hi:[1,1,0]
	v_pk_fma_f32 v[58:59], v[62:63], v[246:247], v[58:59]
	v_pk_fma_f32 v[72:73], v[60:61], v[248:249], v[72:73]
	ds_read_b128 v[154:157], v0 offset:1024
	ds_read_b128 v[246:249], v0 offset:1040
	v_add_f32_e32 v207, v58, v59
	v_add_f32_e32 v209, v72, v73
	ds_read_b128 v[200:203], v0 offset:17664
	ds_read_b128 v[230:233], v0 offset:17680
	s_waitcnt lgkmcnt(12)
	v_pk_mul_f32 v[34:35], v[66:67], v[34:35]
	v_pk_mul_f32 v[36:37], v[64:65], v[36:37]
	v_pk_fma_f32 v[34:35], v[62:63], v[38:39], v[34:35]
	v_pk_fma_f32 v[36:37], v[60:61], v[40:41], v[36:37]
	v_add_f32_e32 v207, v207, v209
	s_waitcnt lgkmcnt(9)
; DI float oct_sum(float v) { v += dpp_f<0xB1>(v); v += dpp_f<0x4E>(v); v += dpp_f<0x141>(v); return v; }
; DI void scan_item(const Params& p, int b, int h, int half, char* smem, unsigned* pgen, unsigned kp) {
;     ...
; #pragma unroll 1
;     for (int sg = 0; sg < SC; sg += 4) {
;       float yy[4];
; #pragma unroll
;       for (int s4 = 0; s4 < 4; ++s4) {
;         const int s = sg + s4;
;         const f32x2* a2 = (const f32x2*)(Al + s * 64 + cg * 8);
;         const f32x2* w2 = (const f32x2*)(Wl + s * 64 + cg * 8);
;         const f32x2* b2 = (const f32x2*)(Bl + s * 64 + cg * 8);
;         const f32x2* k2 = (const f32x2*)(Kl + s * 64 + cg * 8);
;         const f32x2* r2 = (const f32x2*)(Rl + s * 64 + cg * 8);
;         f32x2 o[20];
; #pragma unroll
;         for (int i = 0; i < 4; ++i) { o[i] = a2[i]; o[4 + i] = w2[i]; o[8 + i] = b2[i]; o[12 + i] = k2[i]; o[16 + i] = r2[i]; }
;         const float vr = Vl[s * 64 + 32 * half + rp];
;         f32x2 p0 = St[0] * o[0], p1 = St[1] * o[1];
;         p0 = __builtin_elementwise_fma(St[2], o[2], p0); p1 = __builtin_elementwise_fma(St[3], o[3], p1);
;         const float sa = oct_sum((p0.x + p0.y) + (p1.x + p1.y));
;         const f32x2 sv = {sa, sa}, vv = {vr, vr};
;         f32x2 y0 = {0.f, 0.f}, y1 = {0.f, 0.f};
; #pragma unroll
;         for (int i = 0; i < 4; i += 2) {
;           St[i] = __builtin_elementwise_fma(St[i], o[4 + i], __builtin_elementwise_fma(sv, o[8 + i], vv * o[12 + i]));
;           St[i + 1] = __builtin_elementwise_fma(St[i + 1], o[5 + i], __builtin_elementwise_fma(sv, o[9 + i], vv * o[13 + i]));
;           y0 = __builtin_elementwise_fma(St[i], o[16 + i], y0);
;           y1 = __builtin_elementwise_fma(St[i + 1], o[17 + i], y1);
;         }
;         yy[s4] = oct_sum((y0.x + y0.y) + (y1.x + y1.y));
;       }
;       if (cg == 0) {
; #pragma unroll
;         for (int s4 = 0; s4 < 4; ++s4) Yl[(sg + s4) * 32 + rp] = yy[s4];
;       }
;     }
	v_pk_mul_f32 v[58:59], v[68:69], v[158:159] op_sel_hi:[1,0]
	v_add_f32_e32 v198, v34, v35
	v_add_f32_e32 v199, v36, v37
	v_pk_mul_f32 v[72:73], v[70:71], v[158:159] op_sel_hi:[1,0]
	v_add_f32_e32 v198, v198, v199
	ds_read_b128 v[68:71], v0 offset:9472
	v_pk_mul_f32 v[212:213], v[150:151], v[158:159] op_sel_hi:[1,0]
	v_add_f32_dpp v198, v198, v198 quad_perm:[1,0,3,2] row_mask:0xf bank_mask:0xf bound_ctrl:1
	v_add_f32_dpp v207, v207, v207 quad_perm:[1,0,3,2] row_mask:0xf bank_mask:0xf bound_ctrl:1
	v_pk_mul_f32 v[250:251], v[152:153], v[158:159] op_sel_hi:[1,0]
	v_add_f32_dpp v198, v198, v198 quad_perm:[2,3,0,1] row_mask:0xf bank_mask:0xf bound_ctrl:1
	v_add_f32_dpp v207, v207, v207 quad_perm:[2,3,0,1] row_mask:0xf bank_mask:0xf bound_ctrl:1
	ds_read_b128 v[150:153], v0 offset:9488
	v_add_f32_dpp v198, v198, v198 row_half_mirror row_mask:0xf bank_mask:0xf bound_ctrl:1
	v_add_f32_dpp v207, v207, v207 row_half_mirror row_mask:0xf bank_mask:0xf bound_ctrl:1
	s_and_saveexec_b64 s[4:5], s[12:13]
	ds_write_b32 v162, v207 offset:384
	s_mov_b64 exec, s[4:5]
	s_waitcnt lgkmcnt(9)
	v_pk_fma_f32 v[58:59], v[198:199], v[50:51], v[58:59] op_sel_hi:[0,1,1]
	v_pk_fma_f32 v[72:73], v[198:199], v[52:53], v[72:73] op_sel_hi:[0,1,1]
	s_waitcnt lgkmcnt(7)
	v_pk_fma_f32 v[66:67], v[66:67], v[42:43], v[58:59]
	v_pk_fma_f32 v[64:65], v[64:65], v[44:45], v[72:73]
	v_pk_fma_f32 v[212:213], v[198:199], v[54:55], v[212:213] op_sel_hi:[0,1,1]
	v_pk_fma_f32 v[250:251], v[198:199], v[56:57], v[250:251] op_sel_hi:[0,1,1]
	v_pk_fma_f32 v[62:63], v[62:63], v[46:47], v[212:213]
	v_pk_fma_f32 v[60:61], v[60:61], v[48:49], v[250:251]
	ds_read_b128 v[50:53], v0 offset:21760
	ds_read_b128 v[54:57], v0 offset:21776
	ds_read_b128 v[42:45], v0 offset:5376
	ds_read_b128 v[46:49], v0 offset:5392
	s_waitcnt lgkmcnt(9)
	v_pk_fma_f32 v[58:59], v[66:67], v[154:155], 0 op_sel_hi:[1,1,0]
	v_pk_fma_f32 v[72:73], v[64:65], v[156:157], 0 op_sel_hi:[1,1,0]
	v_pk_fma_f32 v[58:59], v[62:63], v[246:247], v[58:59]
	v_pk_fma_f32 v[72:73], v[60:61], v[248:249], v[72:73]
	ds_read_b128 v[154:157], v0 offset:1280
	ds_read_b128 v[246:249], v0 offset:1296
	v_add_f32_e32 v207, v58, v59
	v_add_f32_e32 v209, v72, v73
	ds_read_b128 v[34:37], v0 offset:17920
	ds_read_b128 v[38:41], v0 offset:17936
	s_waitcnt lgkmcnt(11)
	v_pk_mul_f32 v[200:201], v[66:67], v[200:201]
	v_pk_mul_f32 v[202:203], v[64:65], v[202:203]
	v_pk_fma_f32 v[200:201], v[62:63], v[230:231], v[200:201]
	v_pk_fma_f32 v[202:203], v[60:61], v[232:233], v[202:203]
	v_add_f32_e32 v207, v207, v209
	s_waitcnt lgkmcnt(9)
	v_pk_mul_f32 v[58:59], v[68:69], v[158:159] op_sel:[0,1] op_sel_hi:[1,1]
	v_add_f32_e32 v198, v200, v201
	v_add_f32_e32 v199, v202, v203
	v_pk_mul_f32 v[72:73], v[70:71], v[158:159] op_sel:[0,1] op_sel_hi:[1,1]
	v_add_f32_e32 v198, v198, v199
	ds_read_b128 v[68:71], v0 offset:9728
	v_pk_mul_f32 v[212:213], v[150:151], v[158:159] op_sel:[0,1] op_sel_hi:[1,1]
	v_add_f32_dpp v198, v198, v198 quad_perm:[1,0,3,2] row_mask:0xf bank_mask:0xf bound_ctrl:1
	v_add_f32_dpp v207, v207, v207 quad_perm:[1,0,3,2] row_mask:0xf bank_mask:0xf bound_ctrl:1
	v_pk_mul_f32 v[250:251], v[152:153], v[158:159] op_sel:[0,1] op_sel_hi:[1,1]
	v_add_f32_dpp v198, v198, v198 quad_perm:[2,3,0,1] row_mask:0xf bank_mask:0xf bound_ctrl:1
	v_add_f32_dpp v207, v207, v207 quad_perm:[2,3,0,1] row_mask:0xf bank_mask:0xf bound_ctrl:1
	ds_read_b128 v[150:153], v0 offset:9744
	v_add_f32_dpp v198, v198, v198 row_half_mirror row_mask:0xf bank_mask:0xf bound_ctrl:1
	v_add_f32_dpp v207, v207, v207 row_half_mirror row_mask:0xf bank_mask:0xf bound_ctrl:1
	ds_read2st64_b32 v[158:159], v161 offset0:6 offset1:7
	s_and_saveexec_b64 s[4:5], s[12:13]
	ds_write_b32 v162, v207 offset:512
	s_mov_b64 exec, s[4:5]
	s_waitcnt lgkmcnt(10)
	v_pk_fma_f32 v[58:59], v[198:199], v[50:51], v[58:59] op_sel_hi:[0,1,1]
	v_pk_fma_f32 v[72:73], v[198:199], v[52:53], v[72:73] op_sel_hi:[0,1,1]
	s_waitcnt lgkmcnt(8)
	v_pk_fma_f32 v[66:67], v[66:67], v[42:43], v[58:59]
	v_pk_fma_f32 v[64:65], v[64:65], v[44:45], v[72:73]
	v_pk_fma_f32 v[212:213], v[198:199], v[54:55], v[212:213] op_sel_hi:[0,1,1]
	v_pk_fma_f32 v[250:251], v[198:199], v[56:57], v[250:251] op_sel_hi:[0,1,1]
	v_pk_fma_f32 v[62:63], v[62:63], v[46:47], v[212:213]
	v_pk_fma_f32 v[60:61], v[60:61], v[48:49], v[250:251]
	ds_read_b128 v[50:53], v0 offset:22016
	ds_read_b128 v[54:57], v0 offset:22032
	ds_read_b128 v[42:45], v0 offset:5632
	ds_read_b128 v[46:49], v0 offset:5648
	s_waitcnt lgkmcnt(10)
	v_pk_fma_f32 v[58:59], v[66:67], v[154:155], 0 op_sel_hi:[1,1,0]
	v_pk_fma_f32 v[72:73], v[64:65], v[156:157], 0 op_sel_hi:[1,1,0]
	v_pk_fma_f32 v[58:59], v[62:63], v[246:247], v[58:59]
	v_pk_fma_f32 v[72:73], v[60:61], v[248:249], v[72:73]
	ds_read_b128 v[154:157], v0 offset:1536
	ds_read_b128 v[246:249], v0 offset:1552
	v_add_f32_e32 v207, v58, v59
	v_add_f32_e32 v209, v72, v73
	ds_read_b128 v[200:203], v0 offset:18176
	ds_read_b128 v[230:233], v0 offset:18192
	s_waitcnt lgkmcnt(12)
	v_pk_mul_f32 v[34:35], v[66:67], v[34:35]
	v_pk_mul_f32 v[36:37], v[64:65], v[36:37]
	v_pk_fma_f32 v[34:35], v[62:63], v[38:39], v[34:35]
	v_pk_fma_f32 v[36:37], v[60:61], v[40:41], v[36:37]
	v_add_f32_e32 v207, v207, v209
	s_waitcnt lgkmcnt(9)
; DI float oct_sum(float v) { v += dpp_f<0xB1>(v); v += dpp_f<0x4E>(v); v += dpp_f<0x141>(v); return v; }
; DI void scan_item(const Params& p, int b, int h, int half, char* smem, unsigned* pgen, unsigned kp) {
;     ...
; #pragma unroll 1
;     for (int sg = 0; sg < SC; sg += 4) {
;       float yy[4];
; #pragma unroll
;       for (int s4 = 0; s4 < 4; ++s4) {
;         const int s = sg + s4;
;         const f32x2* a2 = (const f32x2*)(Al + s * 64 + cg * 8);
;         const f32x2* w2 = (const f32x2*)(Wl + s * 64 + cg * 8);
;         const f32x2* b2 = (const f32x2*)(Bl + s * 64 + cg * 8);
;         const f32x2* k2 = (const f32x2*)(Kl + s * 64 + cg * 8);
;         const f32x2* r2 = (const f32x2*)(Rl + s * 64 + cg * 8);
;         f32x2 o[20];
; #pragma unroll
;         for (int i = 0; i < 4; ++i) { o[i] = a2[i]; o[4 + i] = w2[i]; o[8 + i] = b2[i]; o[12 + i] = k2[i]; o[16 + i] = r2[i]; }
;         const float vr = Vl[s * 64 + 32 * half + rp];
;         f32x2 p0 = St[0] * o[0], p1 = St[1] * o[1];
;         p0 = __builtin_elementwise_fma(St[2], o[2], p0); p1 = __builtin_elementwise_fma(St[3], o[3], p1);
;         const float sa = oct_sum((p0.x + p0.y) + (p1.x + p1.y));
;         const f32x2 sv = {sa, sa}, vv = {vr, vr};
;         f32x2 y0 = {0.f, 0.f}, y1 = {0.f, 0.f};
; #pragma unroll
;         for (int i = 0; i < 4; i += 2) {
;           St[i] = __builtin_elementwise_fma(St[i], o[4 + i], __builtin_elementwise_fma(sv, o[8 + i], vv * o[12 + i]));
;           St[i + 1] = __builtin_elementwise_fma(St[i + 1], o[5 + i], __builtin_elementwise_fma(sv, o[9 + i], vv * o[13 + i]));
;           y0 = __builtin_elementwise_fma(St[i], o[16 + i], y0);
;           y1 = __builtin_elementwise_fma(St[i + 1], o[17 + i], y1);
;         }
;         yy[s4] = oct_sum((y0.x + y0.y) + (y1.x + y1.y));
;       }
;       if (cg == 0) {
; #pragma unroll
;         for (int s4 = 0; s4 < 4; ++s4) Yl[(sg + s4) * 32 + rp] = yy[s4];
;       }
;     }
	v_pk_mul_f32 v[58:59], v[68:69], v[158:159] op_sel_hi:[1,0]
	v_add_f32_e32 v198, v34, v35
	v_add_f32_e32 v199, v36, v37
	v_pk_mul_f32 v[72:73], v[70:71], v[158:159] op_sel_hi:[1,0]
	v_add_f32_e32 v198, v198, v199
	ds_read_b128 v[68:71], v0 offset:9984
	v_pk_mul_f32 v[212:213], v[150:151], v[158:159] op_sel_hi:[1,0]
	v_add_f32_dpp v198, v198, v198 quad_perm:[1,0,3,2] row_mask:0xf bank_mask:0xf bound_ctrl:1
	v_add_f32_dpp v207, v207, v207 quad_perm:[1,0,3,2] row_mask:0xf bank_mask:0xf bound_ctrl:1
	v_pk_mul_f32 v[250:251], v[152:153], v[158:159] op_sel_hi:[1,0]
	v_add_f32_dpp v198, v198, v198 quad_perm:[2,3,0,1] row_mask:0xf bank_mask:0xf bound_ctrl:1
	v_add_f32_dpp v207, v207, v207 quad_perm:[2,3,0,1] row_mask:0xf bank_mask:0xf bound_ctrl:1
	ds_read_b128 v[150:153], v0 offset:10000
	v_add_f32_dpp v198, v198, v198 row_half_mirror row_mask:0xf bank_mask:0xf bound_ctrl:1
	v_add_f32_dpp v207, v207, v207 row_half_mirror row_mask:0xf bank_mask:0xf bound_ctrl:1
	s_and_saveexec_b64 s[4:5], s[12:13]
	ds_write_b32 v162, v207 offset:640
	s_mov_b64 exec, s[4:5]
	s_waitcnt lgkmcnt(9)
	v_pk_fma_f32 v[58:59], v[198:199], v[50:51], v[58:59] op_sel_hi:[0,1,1]
	v_pk_fma_f32 v[72:73], v[198:199], v[52:53], v[72:73] op_sel_hi:[0,1,1]
	s_waitcnt lgkmcnt(7)
	v_pk_fma_f32 v[66:67], v[66:67], v[42:43], v[58:59]
	v_pk_fma_f32 v[64:65], v[64:65], v[44:45], v[72:73]
	v_pk_fma_f32 v[212:213], v[198:199], v[54:55], v[212:213] op_sel_hi:[0,1,1]
	v_pk_fma_f32 v[250:251], v[198:199], v[56:57], v[250:251] op_sel_hi:[0,1,1]
	v_pk_fma_f32 v[62:63], v[62:63], v[46:47], v[212:213]
	v_pk_fma_f32 v[60:61], v[60:61], v[48:49], v[250:251]
	ds_read_b128 v[50:53], v0 offset:22272
	ds_read_b128 v[54:57], v0 offset:22288
	ds_read_b128 v[42:45], v0 offset:5888
	ds_read_b128 v[46:49], v0 offset:5904
	s_waitcnt lgkmcnt(9)
	v_pk_fma_f32 v[58:59], v[66:67], v[154:155], 0 op_sel_hi:[1,1,0]
	v_pk_fma_f32 v[72:73], v[64:65], v[156:157], 0 op_sel_hi:[1,1,0]
	v_pk_fma_f32 v[58:59], v[62:63], v[246:247], v[58:59]
	v_pk_fma_f32 v[72:73], v[60:61], v[248:249], v[72:73]
	ds_read_b128 v[154:157], v0 offset:1792
	ds_read_b128 v[246:249], v0 offset:1808
	v_add_f32_e32 v207, v58, v59
	v_add_f32_e32 v209, v72, v73
	ds_read_b128 v[34:37], v0 offset:18432
	ds_read_b128 v[38:41], v0 offset:18448
	s_waitcnt lgkmcnt(11)
	v_pk_mul_f32 v[200:201], v[66:67], v[200:201]
	v_pk_mul_f32 v[202:203], v[64:65], v[202:203]
	v_pk_fma_f32 v[200:201], v[62:63], v[230:231], v[200:201]
	v_pk_fma_f32 v[202:203], v[60:61], v[232:233], v[202:203]
	v_add_f32_e32 v207, v207, v209
	s_waitcnt lgkmcnt(9)
	v_pk_mul_f32 v[58:59], v[68:69], v[158:159] op_sel:[0,1] op_sel_hi:[1,1]
	v_add_f32_e32 v198, v200, v201
	v_add_f32_e32 v199, v202, v203
	v_pk_mul_f32 v[72:73], v[70:71], v[158:159] op_sel:[0,1] op_sel_hi:[1,1]
	v_add_f32_e32 v198, v198, v199
	ds_read_b128 v[68:71], v0 offset:10240
	v_pk_mul_f32 v[212:213], v[150:151], v[158:159] op_sel:[0,1] op_sel_hi:[1,1]
	v_add_f32_dpp v198, v198, v198 quad_perm:[1,0,3,2] row_mask:0xf bank_mask:0xf bound_ctrl:1
	v_add_f32_dpp v207, v207, v207 quad_perm:[1,0,3,2] row_mask:0xf bank_mask:0xf bound_ctrl:1
	v_pk_mul_f32 v[250:251], v[152:153], v[158:159] op_sel:[0,1] op_sel_hi:[1,1]
	v_add_f32_dpp v198, v198, v198 quad_perm:[2,3,0,1] row_mask:0xf bank_mask:0xf bound_ctrl:1
	v_add_f32_dpp v207, v207, v207 quad_perm:[2,3,0,1] row_mask:0xf bank_mask:0xf bound_ctrl:1
	ds_read_b128 v[150:153], v0 offset:10256
	v_add_f32_dpp v198, v198, v198 row_half_mirror row_mask:0xf bank_mask:0xf bound_ctrl:1
	v_add_f32_dpp v207, v207, v207 row_half_mirror row_mask:0xf bank_mask:0xf bound_ctrl:1
	ds_read2st64_b32 v[158:159], v161 offset0:8 offset1:9
	s_and_saveexec_b64 s[4:5], s[12:13]
	ds_write_b32 v162, v207 offset:768
	s_mov_b64 exec, s[4:5]
	s_waitcnt lgkmcnt(10)
	v_pk_fma_f32 v[58:59], v[198:199], v[50:51], v[58:59] op_sel_hi:[0,1,1]
	v_pk_fma_f32 v[72:73], v[198:199], v[52:53], v[72:73] op_sel_hi:[0,1,1]
	s_waitcnt lgkmcnt(8)
	v_pk_fma_f32 v[66:67], v[66:67], v[42:43], v[58:59]
	v_pk_fma_f32 v[64:65], v[64:65], v[44:45], v[72:73]
	v_pk_fma_f32 v[212:213], v[198:199], v[54:55], v[212:213] op_sel_hi:[0,1,1]
	v_pk_fma_f32 v[250:251], v[198:199], v[56:57], v[250:251] op_sel_hi:[0,1,1]
	v_pk_fma_f32 v[62:63], v[62:63], v[46:47], v[212:213]
	v_pk_fma_f32 v[60:61], v[60:61], v[48:49], v[250:251]
	ds_read_b128 v[50:53], v0 offset:22528
	ds_read_b128 v[54:57], v0 offset:22544
	ds_read_b128 v[42:45], v0 offset:6144
	ds_read_b128 v[46:49], v0 offset:6160
	s_waitcnt lgkmcnt(10)
	v_pk_fma_f32 v[58:59], v[66:67], v[154:155], 0 op_sel_hi:[1,1,0]
	v_pk_fma_f32 v[72:73], v[64:65], v[156:157], 0 op_sel_hi:[1,1,0]
	v_pk_fma_f32 v[58:59], v[62:63], v[246:247], v[58:59]
	v_pk_fma_f32 v[72:73], v[60:61], v[248:249], v[72:73]
	ds_read_b128 v[154:157], v0 offset:2048
	ds_read_b128 v[246:249], v0 offset:2064
	v_add_f32_e32 v207, v58, v59
	v_add_f32_e32 v209, v72, v73
	ds_read_b128 v[200:203], v0 offset:18688
	ds_read_b128 v[230:233], v0 offset:18704
	s_waitcnt lgkmcnt(12)
	v_pk_mul_f32 v[34:35], v[66:67], v[34:35]
	v_pk_mul_f32 v[36:37], v[64:65], v[36:37]
	v_pk_fma_f32 v[34:35], v[62:63], v[38:39], v[34:35]
	v_pk_fma_f32 v[36:37], v[60:61], v[40:41], v[36:37]
	v_add_f32_e32 v207, v207, v209
	s_waitcnt lgkmcnt(9)
; DI float oct_sum(float v) { v += dpp_f<0xB1>(v); v += dpp_f<0x4E>(v); v += dpp_f<0x141>(v); return v; }
; DI void scan_item(const Params& p, int b, int h, int half, char* smem, unsigned* pgen, unsigned kp) {
;     ...
; #pragma unroll 1
;     for (int sg = 0; sg < SC; sg += 4) {
;       float yy[4];
; #pragma unroll
;       for (int s4 = 0; s4 < 4; ++s4) {
;         const int s = sg + s4;
;         const f32x2* a2 = (const f32x2*)(Al + s * 64 + cg * 8);
;         const f32x2* w2 = (const f32x2*)(Wl + s * 64 + cg * 8);
;         const f32x2* b2 = (const f32x2*)(Bl + s * 64 + cg * 8);
;         const f32x2* k2 = (const f32x2*)(Kl + s * 64 + cg * 8);
;         const f32x2* r2 = (const f32x2*)(Rl + s * 64 + cg * 8);
;         f32x2 o[20];
; #pragma unroll
;         for (int i = 0; i < 4; ++i) { o[i] = a2[i]; o[4 + i] = w2[i]; o[8 + i] = b2[i]; o[12 + i] = k2[i]; o[16 + i] = r2[i]; }
;         const float vr = Vl[s * 64 + 32 * half + rp];
;         f32x2 p0 = St[0] * o[0], p1 = St[1] * o[1];
;         p0 = __builtin_elementwise_fma(St[2], o[2], p0); p1 = __builtin_elementwise_fma(St[3], o[3], p1);
;         const float sa = oct_sum((p0.x + p0.y) + (p1.x + p1.y));
;         const f32x2 sv = {sa, sa}, vv = {vr, vr};
;         f32x2 y0 = {0.f, 0.f}, y1 = {0.f, 0.f};
; #pragma unroll
;         for (int i = 0; i < 4; i += 2) {
;           St[i] = __builtin_elementwise_fma(St[i], o[4 + i], __builtin_elementwise_fma(sv, o[8 + i], vv * o[12 + i]));
;           St[i + 1] = __builtin_elementwise_fma(St[i + 1], o[5 + i], __builtin_elementwise_fma(sv, o[9 + i], vv * o[13 + i]));
;           y0 = __builtin_elementwise_fma(St[i], o[16 + i], y0);
;           y1 = __builtin_elementwise_fma(St[i + 1], o[17 + i], y1);
;         }
;         yy[s4] = oct_sum((y0.x + y0.y) + (y1.x + y1.y));
;       }
;       if (cg == 0) {
; #pragma unroll
;         for (int s4 = 0; s4 < 4; ++s4) Yl[(sg + s4) * 32 + rp] = yy[s4];
;       }
;     }
	v_pk_mul_f32 v[58:59], v[68:69], v[158:159] op_sel_hi:[1,0]
	v_add_f32_e32 v198, v34, v35
	v_add_f32_e32 v199, v36, v37
	v_pk_mul_f32 v[72:73], v[70:71], v[158:159] op_sel_hi:[1,0]
	v_add_f32_e32 v198, v198, v199
	ds_read_b128 v[68:71], v0 offset:10496
	v_pk_mul_f32 v[212:213], v[150:151], v[158:159] op_sel_hi:[1,0]
	v_add_f32_dpp v198, v198, v198 quad_perm:[1,0,3,2] row_mask:0xf bank_mask:0xf bound_ctrl:1
	v_add_f32_dpp v207, v207, v207 quad_perm:[1,0,3,2] row_mask:0xf bank_mask:0xf bound_ctrl:1
	v_pk_mul_f32 v[250:251], v[152:153], v[158:159] op_sel_hi:[1,0]
	v_add_f32_dpp v198, v198, v198 quad_perm:[2,3,0,1] row_mask:0xf bank_mask:0xf bound_ctrl:1
	v_add_f32_dpp v207, v207, v207 quad_perm:[2,3,0,1] row_mask:0xf bank_mask:0xf bound_ctrl:1
	ds_read_b128 v[150:153], v0 offset:10512
	v_add_f32_dpp v198, v198, v198 row_half_mirror row_mask:0xf bank_mask:0xf bound_ctrl:1
	v_add_f32_dpp v207, v207, v207 row_half_mirror row_mask:0xf bank_mask:0xf bound_ctrl:1
	s_and_saveexec_b64 s[4:5], s[12:13]
	ds_write_b32 v162, v207 offset:896
	s_mov_b64 exec, s[4:5]
	s_waitcnt lgkmcnt(9)
	v_pk_fma_f32 v[58:59], v[198:199], v[50:51], v[58:59] op_sel_hi:[0,1,1]
	v_pk_fma_f32 v[72:73], v[198:199], v[52:53], v[72:73] op_sel_hi:[0,1,1]
	s_waitcnt lgkmcnt(7)
	v_pk_fma_f32 v[66:67], v[66:67], v[42:43], v[58:59]
	v_pk_fma_f32 v[64:65], v[64:65], v[44:45], v[72:73]
	v_pk_fma_f32 v[212:213], v[198:199], v[54:55], v[212:213] op_sel_hi:[0,1,1]
	v_pk_fma_f32 v[250:251], v[198:199], v[56:57], v[250:251] op_sel_hi:[0,1,1]
	v_pk_fma_f32 v[62:63], v[62:63], v[46:47], v[212:213]
	v_pk_fma_f32 v[60:61], v[60:61], v[48:49], v[250:251]
	ds_read_b128 v[50:53], v0 offset:22784
	ds_read_b128 v[54:57], v0 offset:22800
	ds_read_b128 v[42:45], v0 offset:6400
	ds_read_b128 v[46:49], v0 offset:6416
	s_waitcnt lgkmcnt(9)
	v_pk_fma_f32 v[58:59], v[66:67], v[154:155], 0 op_sel_hi:[1,1,0]
	v_pk_fma_f32 v[72:73], v[64:65], v[156:157], 0 op_sel_hi:[1,1,0]
	v_pk_fma_f32 v[58:59], v[62:63], v[246:247], v[58:59]
	v_pk_fma_f32 v[72:73], v[60:61], v[248:249], v[72:73]
	ds_read_b128 v[154:157], v0 offset:2304
	ds_read_b128 v[246:249], v0 offset:2320
	v_add_f32_e32 v207, v58, v59
	v_add_f32_e32 v209, v72, v73
	ds_read_b128 v[34:37], v0 offset:18944
	ds_read_b128 v[38:41], v0 offset:18960
	s_waitcnt lgkmcnt(11)
	v_pk_mul_f32 v[200:201], v[66:67], v[200:201]
	v_pk_mul_f32 v[202:203], v[64:65], v[202:203]
	v_pk_fma_f32 v[200:201], v[62:63], v[230:231], v[200:201]
	v_pk_fma_f32 v[202:203], v[60:61], v[232:233], v[202:203]
	v_add_f32_e32 v207, v207, v209
	s_waitcnt lgkmcnt(9)
	v_pk_mul_f32 v[58:59], v[68:69], v[158:159] op_sel:[0,1] op_sel_hi:[1,1]
	v_add_f32_e32 v198, v200, v201
	v_add_f32_e32 v199, v202, v203
	v_pk_mul_f32 v[72:73], v[70:71], v[158:159] op_sel:[0,1] op_sel_hi:[1,1]
	v_add_f32_e32 v198, v198, v199
	ds_read_b128 v[68:71], v0 offset:10752
	v_pk_mul_f32 v[212:213], v[150:151], v[158:159] op_sel:[0,1] op_sel_hi:[1,1]
	v_add_f32_dpp v198, v198, v198 quad_perm:[1,0,3,2] row_mask:0xf bank_mask:0xf bound_ctrl:1
	v_add_f32_dpp v207, v207, v207 quad_perm:[1,0,3,2] row_mask:0xf bank_mask:0xf bound_ctrl:1
	v_pk_mul_f32 v[250:251], v[152:153], v[158:159] op_sel:[0,1] op_sel_hi:[1,1]
	v_add_f32_dpp v198, v198, v198 quad_perm:[2,3,0,1] row_mask:0xf bank_mask:0xf bound_ctrl:1
	v_add_f32_dpp v207, v207, v207 quad_perm:[2,3,0,1] row_mask:0xf bank_mask:0xf bound_ctrl:1
	ds_read_b128 v[150:153], v0 offset:10768
	v_add_f32_dpp v198, v198, v198 row_half_mirror row_mask:0xf bank_mask:0xf bound_ctrl:1
	v_add_f32_dpp v207, v207, v207 row_half_mirror row_mask:0xf bank_mask:0xf bound_ctrl:1
	ds_read2st64_b32 v[158:159], v161 offset0:10 offset1:11
	s_and_saveexec_b64 s[4:5], s[12:13]
	ds_write_b32 v162, v207 offset:1024
	s_mov_b64 exec, s[4:5]
	s_waitcnt lgkmcnt(10)
	v_pk_fma_f32 v[58:59], v[198:199], v[50:51], v[58:59] op_sel_hi:[0,1,1]
	v_pk_fma_f32 v[72:73], v[198:199], v[52:53], v[72:73] op_sel_hi:[0,1,1]
	s_waitcnt lgkmcnt(8)
	v_pk_fma_f32 v[66:67], v[66:67], v[42:43], v[58:59]
	v_pk_fma_f32 v[64:65], v[64:65], v[44:45], v[72:73]
	v_pk_fma_f32 v[212:213], v[198:199], v[54:55], v[212:213] op_sel_hi:[0,1,1]
	v_pk_fma_f32 v[250:251], v[198:199], v[56:57], v[250:251] op_sel_hi:[0,1,1]
	v_pk_fma_f32 v[62:63], v[62:63], v[46:47], v[212:213]
	v_pk_fma_f32 v[60:61], v[60:61], v[48:49], v[250:251]
	ds_read_b128 v[50:53], v0 offset:23040
	ds_read_b128 v[54:57], v0 offset:23056
	ds_read_b128 v[42:45], v0 offset:6656
	ds_read_b128 v[46:49], v0 offset:6672
	s_waitcnt lgkmcnt(10)
	v_pk_fma_f32 v[58:59], v[66:67], v[154:155], 0 op_sel_hi:[1,1,0]
	v_pk_fma_f32 v[72:73], v[64:65], v[156:157], 0 op_sel_hi:[1,1,0]
	v_pk_fma_f32 v[58:59], v[62:63], v[246:247], v[58:59]
	v_pk_fma_f32 v[72:73], v[60:61], v[248:249], v[72:73]
	ds_read_b128 v[154:157], v0 offset:2560
	ds_read_b128 v[246:249], v0 offset:2576
	v_add_f32_e32 v207, v58, v59
	v_add_f32_e32 v209, v72, v73
	ds_read_b128 v[200:203], v0 offset:19200
	ds_read_b128 v[230:233], v0 offset:19216
	s_waitcnt lgkmcnt(12)
	v_pk_mul_f32 v[34:35], v[66:67], v[34:35]
	v_pk_mul_f32 v[36:37], v[64:65], v[36:37]
	v_pk_fma_f32 v[34:35], v[62:63], v[38:39], v[34:35]
	v_pk_fma_f32 v[36:37], v[60:61], v[40:41], v[36:37]
	v_add_f32_e32 v207, v207, v209
	s_waitcnt lgkmcnt(9)
; DI float oct_sum(float v) { v += dpp_f<0xB1>(v); v += dpp_f<0x4E>(v); v += dpp_f<0x141>(v); return v; }
; DI void scan_item(const Params& p, int b, int h, int half, char* smem, unsigned* pgen, unsigned kp) {
;     ...
; #pragma unroll 1
;     for (int sg = 0; sg < SC; sg += 4) {
;       float yy[4];
; #pragma unroll
;       for (int s4 = 0; s4 < 4; ++s4) {
;         const int s = sg + s4;
;         const f32x2* a2 = (const f32x2*)(Al + s * 64 + cg * 8);
;         const f32x2* w2 = (const f32x2*)(Wl + s * 64 + cg * 8);
;         const f32x2* b2 = (const f32x2*)(Bl + s * 64 + cg * 8);
;         const f32x2* k2 = (const f32x2*)(Kl + s * 64 + cg * 8);
;         const f32x2* r2 = (const f32x2*)(Rl + s * 64 + cg * 8);
;         f32x2 o[20];
; #pragma unroll
;         for (int i = 0; i < 4; ++i) { o[i] = a2[i]; o[4 + i] = w2[i]; o[8 + i] = b2[i]; o[12 + i] = k2[i]; o[16 + i] = r2[i]; }
;         const float vr = Vl[s * 64 + 32 * half + rp];
;         f32x2 p0 = St[0] * o[0], p1 = St[1] * o[1];
;         p0 = __builtin_elementwise_fma(St[2], o[2], p0); p1 = __builtin_elementwise_fma(St[3], o[3], p1);
;         const float sa = oct_sum((p0.x + p0.y) + (p1.x + p1.y));
;         const f32x2 sv = {sa, sa}, vv = {vr, vr};
;         f32x2 y0 = {0.f, 0.f}, y1 = {0.f, 0.f};
; #pragma unroll
;         for (int i = 0; i < 4; i += 2) {
;           St[i] = __builtin_elementwise_fma(St[i], o[4 + i], __builtin_elementwise_fma(sv, o[8 + i], vv * o[12 + i]));
;           St[i + 1] = __builtin_elementwise_fma(St[i + 1], o[5 + i], __builtin_elementwise_fma(sv, o[9 + i], vv * o[13 + i]));
;           y0 = __builtin_elementwise_fma(St[i], o[16 + i], y0);
;           y1 = __builtin_elementwise_fma(St[i + 1], o[17 + i], y1);
;         }
;         yy[s4] = oct_sum((y0.x + y0.y) + (y1.x + y1.y));
;       }
;       if (cg == 0) {
; #pragma unroll
;         for (int s4 = 0; s4 < 4; ++s4) Yl[(sg + s4) * 32 + rp] = yy[s4];
;       }
;     }
	v_pk_mul_f32 v[58:59], v[68:69], v[158:159] op_sel_hi:[1,0]
	v_add_f32_e32 v198, v34, v35
	v_add_f32_e32 v199, v36, v37
	v_pk_mul_f32 v[72:73], v[70:71], v[158:159] op_sel_hi:[1,0]
	v_add_f32_e32 v198, v198, v199
	ds_read_b128 v[68:71], v0 offset:11008
	v_pk_mul_f32 v[212:213], v[150:151], v[158:159] op_sel_hi:[1,0]
	v_add_f32_dpp v198, v198, v198 quad_perm:[1,0,3,2] row_mask:0xf bank_mask:0xf bound_ctrl:1
	v_add_f32_dpp v207, v207, v207 quad_perm:[1,0,3,2] row_mask:0xf bank_mask:0xf bound_ctrl:1
	v_pk_mul_f32 v[250:251], v[152:153], v[158:159] op_sel_hi:[1,0]
	v_add_f32_dpp v198, v198, v198 quad_perm:[2,3,0,1] row_mask:0xf bank_mask:0xf bound_ctrl:1
	v_add_f32_dpp v207, v207, v207 quad_perm:[2,3,0,1] row_mask:0xf bank_mask:0xf bound_ctrl:1
	ds_read_b128 v[150:153], v0 offset:11024
	v_add_f32_dpp v198, v198, v198 row_half_mirror row_mask:0xf bank_mask:0xf bound_ctrl:1
	v_add_f32_dpp v207, v207, v207 row_half_mirror row_mask:0xf bank_mask:0xf bound_ctrl:1
	s_and_saveexec_b64 s[4:5], s[12:13]
	ds_write_b32 v162, v207 offset:1152
	s_mov_b64 exec, s[4:5]
	s_waitcnt lgkmcnt(9)
	v_pk_fma_f32 v[58:59], v[198:199], v[50:51], v[58:59] op_sel_hi:[0,1,1]
	v_pk_fma_f32 v[72:73], v[198:199], v[52:53], v[72:73] op_sel_hi:[0,1,1]
	s_waitcnt lgkmcnt(7)
	v_pk_fma_f32 v[66:67], v[66:67], v[42:43], v[58:59]
	v_pk_fma_f32 v[64:65], v[64:65], v[44:45], v[72:73]
	v_pk_fma_f32 v[212:213], v[198:199], v[54:55], v[212:213] op_sel_hi:[0,1,1]
	v_pk_fma_f32 v[250:251], v[198:199], v[56:57], v[250:251] op_sel_hi:[0,1,1]
	v_pk_fma_f32 v[62:63], v[62:63], v[46:47], v[212:213]
	v_pk_fma_f32 v[60:61], v[60:61], v[48:49], v[250:251]
	ds_read_b128 v[50:53], v0 offset:23296
	ds_read_b128 v[54:57], v0 offset:23312
	ds_read_b128 v[42:45], v0 offset:6912
	ds_read_b128 v[46:49], v0 offset:6928
	s_waitcnt lgkmcnt(9)
	v_pk_fma_f32 v[58:59], v[66:67], v[154:155], 0 op_sel_hi:[1,1,0]
	v_pk_fma_f32 v[72:73], v[64:65], v[156:157], 0 op_sel_hi:[1,1,0]
	v_pk_fma_f32 v[58:59], v[62:63], v[246:247], v[58:59]
	v_pk_fma_f32 v[72:73], v[60:61], v[248:249], v[72:73]
	ds_read_b128 v[154:157], v0 offset:2816
	ds_read_b128 v[246:249], v0 offset:2832
	v_add_f32_e32 v207, v58, v59
	v_add_f32_e32 v209, v72, v73
	ds_read_b128 v[34:37], v0 offset:19456
	ds_read_b128 v[38:41], v0 offset:19472
	s_waitcnt lgkmcnt(11)
	v_pk_mul_f32 v[200:201], v[66:67], v[200:201]
	v_pk_mul_f32 v[202:203], v[64:65], v[202:203]
	v_pk_fma_f32 v[200:201], v[62:63], v[230:231], v[200:201]
	v_pk_fma_f32 v[202:203], v[60:61], v[232:233], v[202:203]
	v_add_f32_e32 v207, v207, v209
	s_waitcnt lgkmcnt(9)
	v_pk_mul_f32 v[58:59], v[68:69], v[158:159] op_sel:[0,1] op_sel_hi:[1,1]
	v_add_f32_e32 v198, v200, v201
	v_add_f32_e32 v199, v202, v203
	v_pk_mul_f32 v[72:73], v[70:71], v[158:159] op_sel:[0,1] op_sel_hi:[1,1]
	v_add_f32_e32 v198, v198, v199
	ds_read_b128 v[68:71], v0 offset:11264
	v_pk_mul_f32 v[212:213], v[150:151], v[158:159] op_sel:[0,1] op_sel_hi:[1,1]
	v_add_f32_dpp v198, v198, v198 quad_perm:[1,0,3,2] row_mask:0xf bank_mask:0xf bound_ctrl:1
	v_add_f32_dpp v207, v207, v207 quad_perm:[1,0,3,2] row_mask:0xf bank_mask:0xf bound_ctrl:1
	v_pk_mul_f32 v[250:251], v[152:153], v[158:159] op_sel:[0,1] op_sel_hi:[1,1]
	v_add_f32_dpp v198, v198, v198 quad_perm:[2,3,0,1] row_mask:0xf bank_mask:0xf bound_ctrl:1
	v_add_f32_dpp v207, v207, v207 quad_perm:[2,3,0,1] row_mask:0xf bank_mask:0xf bound_ctrl:1
	ds_read_b128 v[150:153], v0 offset:11280
	v_add_f32_dpp v198, v198, v198 row_half_mirror row_mask:0xf bank_mask:0xf bound_ctrl:1
	v_add_f32_dpp v207, v207, v207 row_half_mirror row_mask:0xf bank_mask:0xf bound_ctrl:1
	ds_read2st64_b32 v[158:159], v161 offset0:12 offset1:13
	s_and_saveexec_b64 s[4:5], s[12:13]
	ds_write_b32 v162, v207 offset:1280
	s_mov_b64 exec, s[4:5]
	s_waitcnt lgkmcnt(10)
	v_pk_fma_f32 v[58:59], v[198:199], v[50:51], v[58:59] op_sel_hi:[0,1,1]
	v_pk_fma_f32 v[72:73], v[198:199], v[52:53], v[72:73] op_sel_hi:[0,1,1]
	s_waitcnt lgkmcnt(8)
	v_pk_fma_f32 v[66:67], v[66:67], v[42:43], v[58:59]
	v_pk_fma_f32 v[64:65], v[64:65], v[44:45], v[72:73]
	v_pk_fma_f32 v[212:213], v[198:199], v[54:55], v[212:213] op_sel_hi:[0,1,1]
	v_pk_fma_f32 v[250:251], v[198:199], v[56:57], v[250:251] op_sel_hi:[0,1,1]
	v_pk_fma_f32 v[62:63], v[62:63], v[46:47], v[212:213]
	v_pk_fma_f32 v[60:61], v[60:61], v[48:49], v[250:251]
	ds_read_b128 v[50:53], v0 offset:23552
	ds_read_b128 v[54:57], v0 offset:23568
	ds_read_b128 v[42:45], v0 offset:7168
	ds_read_b128 v[46:49], v0 offset:7184
	s_waitcnt lgkmcnt(10)
	v_pk_fma_f32 v[58:59], v[66:67], v[154:155], 0 op_sel_hi:[1,1,0]
	v_pk_fma_f32 v[72:73], v[64:65], v[156:157], 0 op_sel_hi:[1,1,0]
	v_pk_fma_f32 v[58:59], v[62:63], v[246:247], v[58:59]
	v_pk_fma_f32 v[72:73], v[60:61], v[248:249], v[72:73]
	ds_read_b128 v[154:157], v0 offset:3072
	ds_read_b128 v[246:249], v0 offset:3088
	v_add_f32_e32 v207, v58, v59
	v_add_f32_e32 v209, v72, v73
	ds_read_b128 v[200:203], v0 offset:19712
	ds_read_b128 v[230:233], v0 offset:19728
	s_waitcnt lgkmcnt(12)
	v_pk_mul_f32 v[34:35], v[66:67], v[34:35]
	v_pk_mul_f32 v[36:37], v[64:65], v[36:37]
	v_pk_fma_f32 v[34:35], v[62:63], v[38:39], v[34:35]
	v_pk_fma_f32 v[36:37], v[60:61], v[40:41], v[36:37]
	v_add_f32_e32 v207, v207, v209
	s_waitcnt lgkmcnt(9)
; DI float oct_sum(float v) { v += dpp_f<0xB1>(v); v += dpp_f<0x4E>(v); v += dpp_f<0x141>(v); return v; }
; DI void scan_item(const Params& p, int b, int h, int half, char* smem, unsigned* pgen, unsigned kp) {
;     ...
; #pragma unroll 1
;     for (int sg = 0; sg < SC; sg += 4) {
;       float yy[4];
; #pragma unroll
;       for (int s4 = 0; s4 < 4; ++s4) {
;         const int s = sg + s4;
;         const f32x2* a2 = (const f32x2*)(Al + s * 64 + cg * 8);
;         const f32x2* w2 = (const f32x2*)(Wl + s * 64 + cg * 8);
;         const f32x2* b2 = (const f32x2*)(Bl + s * 64 + cg * 8);
;         const f32x2* k2 = (const f32x2*)(Kl + s * 64 + cg * 8);
;         const f32x2* r2 = (const f32x2*)(Rl + s * 64 + cg * 8);
;         f32x2 o[20];
; #pragma unroll
;         for (int i = 0; i < 4; ++i) { o[i] = a2[i]; o[4 + i] = w2[i]; o[8 + i] = b2[i]; o[12 + i] = k2[i]; o[16 + i] = r2[i]; }
;         const float vr = Vl[s * 64 + 32 * half + rp];
;         f32x2 p0 = St[0] * o[0], p1 = St[1] * o[1];
;         p0 = __builtin_elementwise_fma(St[2], o[2], p0); p1 = __builtin_elementwise_fma(St[3], o[3], p1);
;         const float sa = oct_sum((p0.x + p0.y) + (p1.x + p1.y));
;         const f32x2 sv = {sa, sa}, vv = {vr, vr};
;         f32x2 y0 = {0.f, 0.f}, y1 = {0.f, 0.f};
; #pragma unroll
;         for (int i = 0; i < 4; i += 2) {
;           St[i] = __builtin_elementwise_fma(St[i], o[4 + i], __builtin_elementwise_fma(sv, o[8 + i], vv * o[12 + i]));
;           St[i + 1] = __builtin_elementwise_fma(St[i + 1], o[5 + i], __builtin_elementwise_fma(sv, o[9 + i], vv * o[13 + i]));
;           y0 = __builtin_elementwise_fma(St[i], o[16 + i], y0);
;           y1 = __builtin_elementwise_fma(St[i + 1], o[17 + i], y1);
;         }
;         yy[s4] = oct_sum((y0.x + y0.y) + (y1.x + y1.y));
;       }
;       if (cg == 0) {
; #pragma unroll
;         for (int s4 = 0; s4 < 4; ++s4) Yl[(sg + s4) * 32 + rp] = yy[s4];
;       }
;     }
	v_pk_mul_f32 v[58:59], v[68:69], v[158:159] op_sel_hi:[1,0]
	v_add_f32_e32 v198, v34, v35
	v_add_f32_e32 v199, v36, v37
	v_pk_mul_f32 v[72:73], v[70:71], v[158:159] op_sel_hi:[1,0]
	v_add_f32_e32 v198, v198, v199
	ds_read_b128 v[68:71], v0 offset:11520
	v_pk_mul_f32 v[212:213], v[150:151], v[158:159] op_sel_hi:[1,0]
	v_add_f32_dpp v198, v198, v198 quad_perm:[1,0,3,2] row_mask:0xf bank_mask:0xf bound_ctrl:1
	v_add_f32_dpp v207, v207, v207 quad_perm:[1,0,3,2] row_mask:0xf bank_mask:0xf bound_ctrl:1
	v_pk_mul_f32 v[250:251], v[152:153], v[158:159] op_sel_hi:[1,0]
	v_add_f32_dpp v198, v198, v198 quad_perm:[2,3,0,1] row_mask:0xf bank_mask:0xf bound_ctrl:1
	v_add_f32_dpp v207, v207, v207 quad_perm:[2,3,0,1] row_mask:0xf bank_mask:0xf bound_ctrl:1
	ds_read_b128 v[150:153], v0 offset:11536
	v_add_f32_dpp v198, v198, v198 row_half_mirror row_mask:0xf bank_mask:0xf bound_ctrl:1
	v_add_f32_dpp v207, v207, v207 row_half_mirror row_mask:0xf bank_mask:0xf bound_ctrl:1
	s_and_saveexec_b64 s[4:5], s[12:13]
	ds_write_b32 v162, v207 offset:1408
	s_mov_b64 exec, s[4:5]
	s_waitcnt lgkmcnt(9)
	v_pk_fma_f32 v[58:59], v[198:199], v[50:51], v[58:59] op_sel_hi:[0,1,1]
	v_pk_fma_f32 v[72:73], v[198:199], v[52:53], v[72:73] op_sel_hi:[0,1,1]
	s_waitcnt lgkmcnt(7)
	v_pk_fma_f32 v[66:67], v[66:67], v[42:43], v[58:59]
	v_pk_fma_f32 v[64:65], v[64:65], v[44:45], v[72:73]
	v_pk_fma_f32 v[212:213], v[198:199], v[54:55], v[212:213] op_sel_hi:[0,1,1]
	v_pk_fma_f32 v[250:251], v[198:199], v[56:57], v[250:251] op_sel_hi:[0,1,1]
	v_pk_fma_f32 v[62:63], v[62:63], v[46:47], v[212:213]
	v_pk_fma_f32 v[60:61], v[60:61], v[48:49], v[250:251]
	ds_read_b128 v[50:53], v0 offset:23808
	ds_read_b128 v[54:57], v0 offset:23824
	ds_read_b128 v[42:45], v0 offset:7424
	ds_read_b128 v[46:49], v0 offset:7440
	s_waitcnt lgkmcnt(9)
	v_pk_fma_f32 v[58:59], v[66:67], v[154:155], 0 op_sel_hi:[1,1,0]
	v_pk_fma_f32 v[72:73], v[64:65], v[156:157], 0 op_sel_hi:[1,1,0]
	v_pk_fma_f32 v[58:59], v[62:63], v[246:247], v[58:59]
	v_pk_fma_f32 v[72:73], v[60:61], v[248:249], v[72:73]
	ds_read_b128 v[154:157], v0 offset:3328
	ds_read_b128 v[246:249], v0 offset:3344
	v_add_f32_e32 v207, v58, v59
	v_add_f32_e32 v209, v72, v73
	ds_read_b128 v[34:37], v0 offset:19968
	ds_read_b128 v[38:41], v0 offset:19984
	s_waitcnt lgkmcnt(11)
	v_pk_mul_f32 v[200:201], v[66:67], v[200:201]
	v_pk_mul_f32 v[202:203], v[64:65], v[202:203]
	v_pk_fma_f32 v[200:201], v[62:63], v[230:231], v[200:201]
	v_pk_fma_f32 v[202:203], v[60:61], v[232:233], v[202:203]
	v_add_f32_e32 v207, v207, v209
	s_waitcnt lgkmcnt(9)
	v_pk_mul_f32 v[58:59], v[68:69], v[158:159] op_sel:[0,1] op_sel_hi:[1,1]
	v_add_f32_e32 v198, v200, v201
	v_add_f32_e32 v199, v202, v203
	v_pk_mul_f32 v[72:73], v[70:71], v[158:159] op_sel:[0,1] op_sel_hi:[1,1]
	v_add_f32_e32 v198, v198, v199
	ds_read_b128 v[68:71], v0 offset:11776
	v_pk_mul_f32 v[212:213], v[150:151], v[158:159] op_sel:[0,1] op_sel_hi:[1,1]
	v_add_f32_dpp v198, v198, v198 quad_perm:[1,0,3,2] row_mask:0xf bank_mask:0xf bound_ctrl:1
	v_add_f32_dpp v207, v207, v207 quad_perm:[1,0,3,2] row_mask:0xf bank_mask:0xf bound_ctrl:1
	v_pk_mul_f32 v[250:251], v[152:153], v[158:159] op_sel:[0,1] op_sel_hi:[1,1]
	v_add_f32_dpp v198, v198, v198 quad_perm:[2,3,0,1] row_mask:0xf bank_mask:0xf bound_ctrl:1
	v_add_f32_dpp v207, v207, v207 quad_perm:[2,3,0,1] row_mask:0xf bank_mask:0xf bound_ctrl:1
	ds_read_b128 v[150:153], v0 offset:11792
	v_add_f32_dpp v198, v198, v198 row_half_mirror row_mask:0xf bank_mask:0xf bound_ctrl:1
	v_add_f32_dpp v207, v207, v207 row_half_mirror row_mask:0xf bank_mask:0xf bound_ctrl:1
	ds_read2st64_b32 v[158:159], v161 offset0:14 offset1:15
	s_and_saveexec_b64 s[4:5], s[12:13]
	ds_write_b32 v162, v207 offset:1536
	s_mov_b64 exec, s[4:5]
	s_waitcnt lgkmcnt(10)
	v_pk_fma_f32 v[58:59], v[198:199], v[50:51], v[58:59] op_sel_hi:[0,1,1]
	v_pk_fma_f32 v[72:73], v[198:199], v[52:53], v[72:73] op_sel_hi:[0,1,1]
	s_waitcnt lgkmcnt(8)
	v_pk_fma_f32 v[66:67], v[66:67], v[42:43], v[58:59]
	v_pk_fma_f32 v[64:65], v[64:65], v[44:45], v[72:73]
	v_pk_fma_f32 v[212:213], v[198:199], v[54:55], v[212:213] op_sel_hi:[0,1,1]
	v_pk_fma_f32 v[250:251], v[198:199], v[56:57], v[250:251] op_sel_hi:[0,1,1]
	v_pk_fma_f32 v[62:63], v[62:63], v[46:47], v[212:213]
	v_pk_fma_f32 v[60:61], v[60:61], v[48:49], v[250:251]
	ds_read_b128 v[50:53], v0 offset:24064
	ds_read_b128 v[54:57], v0 offset:24080
	ds_read_b128 v[42:45], v0 offset:7680
	ds_read_b128 v[46:49], v0 offset:7696
	s_waitcnt lgkmcnt(10)
	v_pk_fma_f32 v[58:59], v[66:67], v[154:155], 0 op_sel_hi:[1,1,0]
	v_pk_fma_f32 v[72:73], v[64:65], v[156:157], 0 op_sel_hi:[1,1,0]
	v_pk_fma_f32 v[58:59], v[62:63], v[246:247], v[58:59]
	v_pk_fma_f32 v[72:73], v[60:61], v[248:249], v[72:73]
	ds_read_b128 v[154:157], v0 offset:3584
	ds_read_b128 v[246:249], v0 offset:3600
	v_add_f32_e32 v207, v58, v59
	v_add_f32_e32 v209, v72, v73
	ds_read_b128 v[200:203], v0 offset:20224
	ds_read_b128 v[230:233], v0 offset:20240
	s_waitcnt lgkmcnt(12)
; DI float oct_sum(float v) { v += dpp_f<0xB1>(v); v += dpp_f<0x4E>(v); v += dpp_f<0x141>(v); return v; }
; DI void scan_item(const Params& p, int b, int h, int half, char* smem, unsigned* pgen, unsigned kp) {
;     ...
; #pragma unroll 1
;     for (int sg = 0; sg < SC; sg += 4) {
;       float yy[4];
; #pragma unroll
;       for (int s4 = 0; s4 < 4; ++s4) {
;         const int s = sg + s4;
;         const f32x2* a2 = (const f32x2*)(Al + s * 64 + cg * 8);
;         const f32x2* w2 = (const f32x2*)(Wl + s * 64 + cg * 8);
;         const f32x2* b2 = (const f32x2*)(Bl + s * 64 + cg * 8);
;         const f32x2* k2 = (const f32x2*)(Kl + s * 64 + cg * 8);
;         const f32x2* r2 = (const f32x2*)(Rl + s * 64 + cg * 8);
;         f32x2 o[20];
; #pragma unroll
;         for (int i = 0; i < 4; ++i) { o[i] = a2[i]; o[4 + i] = w2[i]; o[8 + i] = b2[i]; o[12 + i] = k2[i]; o[16 + i] = r2[i]; }
;         const float vr = Vl[s * 64 + 32 * half + rp];
;         f32x2 p0 = St[0] * o[0], p1 = St[1] * o[1];
;         p0 = __builtin_elementwise_fma(St[2], o[2], p0); p1 = __builtin_elementwise_fma(St[3], o[3], p1);
;         const float sa = oct_sum((p0.x + p0.y) + (p1.x + p1.y));
;         const f32x2 sv = {sa, sa}, vv = {vr, vr};
;         f32x2 y0 = {0.f, 0.f}, y1 = {0.f, 0.f};
; #pragma unroll
;         for (int i = 0; i < 4; i += 2) {
;           St[i] = __builtin_elementwise_fma(St[i], o[4 + i], __builtin_elementwise_fma(sv, o[8 + i], vv * o[12 + i]));
;           St[i + 1] = __builtin_elementwise_fma(St[i + 1], o[5 + i], __builtin_elementwise_fma(sv, o[9 + i], vv * o[13 + i]));
;           y0 = __builtin_elementwise_fma(St[i], o[16 + i], y0);
;           y1 = __builtin_elementwise_fma(St[i + 1], o[17 + i], y1);
;         }
;         yy[s4] = oct_sum((y0.x + y0.y) + (y1.x + y1.y));
;       }
;       if (cg == 0) {
; #pragma unroll
;         for (int s4 = 0; s4 < 4; ++s4) Yl[(sg + s4) * 32 + rp] = yy[s4];
;       }
;     }
	v_pk_mul_f32 v[34:35], v[66:67], v[34:35]
	v_pk_mul_f32 v[36:37], v[64:65], v[36:37]
	v_pk_fma_f32 v[34:35], v[62:63], v[38:39], v[34:35]
	v_pk_fma_f32 v[36:37], v[60:61], v[40:41], v[36:37]
	v_add_f32_e32 v207, v207, v209
	s_waitcnt lgkmcnt(9)
	v_pk_mul_f32 v[58:59], v[68:69], v[158:159] op_sel_hi:[1,0]
	v_add_f32_e32 v198, v34, v35
	v_add_f32_e32 v199, v36, v37
	v_pk_mul_f32 v[72:73], v[70:71], v[158:159] op_sel_hi:[1,0]
	v_add_f32_e32 v198, v198, v199
	ds_read_b128 v[68:71], v0 offset:12032
	v_pk_mul_f32 v[212:213], v[150:151], v[158:159] op_sel_hi:[1,0]
	v_add_f32_dpp v198, v198, v198 quad_perm:[1,0,3,2] row_mask:0xf bank_mask:0xf bound_ctrl:1
	v_add_f32_dpp v207, v207, v207 quad_perm:[1,0,3,2] row_mask:0xf bank_mask:0xf bound_ctrl:1
	v_pk_mul_f32 v[250:251], v[152:153], v[158:159] op_sel_hi:[1,0]
	v_add_f32_dpp v198, v198, v198 quad_perm:[2,3,0,1] row_mask:0xf bank_mask:0xf bound_ctrl:1
	v_add_f32_dpp v207, v207, v207 quad_perm:[2,3,0,1] row_mask:0xf bank_mask:0xf bound_ctrl:1
	ds_read_b128 v[150:153], v0 offset:12048
	v_add_f32_dpp v198, v198, v198 row_half_mirror row_mask:0xf bank_mask:0xf bound_ctrl:1
	v_add_f32_dpp v207, v207, v207 row_half_mirror row_mask:0xf bank_mask:0xf bound_ctrl:1
	s_and_saveexec_b64 s[4:5], s[12:13]
	ds_write_b32 v162, v207 offset:1664
	s_mov_b64 exec, s[4:5]
	s_waitcnt lgkmcnt(9)
	v_pk_fma_f32 v[58:59], v[198:199], v[50:51], v[58:59] op_sel_hi:[0,1,1]
	v_pk_fma_f32 v[72:73], v[198:199], v[52:53], v[72:73] op_sel_hi:[0,1,1]
	s_waitcnt lgkmcnt(7)
	v_pk_fma_f32 v[66:67], v[66:67], v[42:43], v[58:59]
	v_pk_fma_f32 v[64:65], v[64:65], v[44:45], v[72:73]
	v_pk_fma_f32 v[212:213], v[198:199], v[54:55], v[212:213] op_sel_hi:[0,1,1]
	v_pk_fma_f32 v[250:251], v[198:199], v[56:57], v[250:251] op_sel_hi:[0,1,1]
	v_pk_fma_f32 v[62:63], v[62:63], v[46:47], v[212:213]
	v_pk_fma_f32 v[60:61], v[60:61], v[48:49], v[250:251]
	ds_read_b128 v[50:53], v0 offset:24320
	ds_read_b128 v[54:57], v0 offset:24336
	ds_read_b128 v[42:45], v0 offset:7936
	ds_read_b128 v[46:49], v0 offset:7952
	s_waitcnt lgkmcnt(9)
	v_pk_fma_f32 v[58:59], v[66:67], v[154:155], 0 op_sel_hi:[1,1,0]
	v_pk_fma_f32 v[72:73], v[64:65], v[156:157], 0 op_sel_hi:[1,1,0]
	v_pk_fma_f32 v[58:59], v[62:63], v[246:247], v[58:59]
	v_pk_fma_f32 v[72:73], v[60:61], v[248:249], v[72:73]
	ds_read_b128 v[154:157], v0 offset:3840
	ds_read_b128 v[246:249], v0 offset:3856
	v_add_f32_e32 v207, v58, v59
	v_add_f32_e32 v209, v72, v73
	s_waitcnt lgkmcnt(9)
	v_pk_mul_f32 v[200:201], v[66:67], v[200:201]
	v_pk_mul_f32 v[202:203], v[64:65], v[202:203]
	v_pk_fma_f32 v[200:201], v[62:63], v[230:231], v[200:201]
	v_pk_fma_f32 v[202:203], v[60:61], v[232:233], v[202:203]
	v_add_f32_e32 v207, v207, v209
	s_waitcnt lgkmcnt(7)
	v_pk_mul_f32 v[58:59], v[68:69], v[158:159] op_sel:[0,1] op_sel_hi:[1,1]
	v_add_f32_e32 v198, v200, v201
	v_add_f32_e32 v199, v202, v203
	v_pk_mul_f32 v[72:73], v[70:71], v[158:159] op_sel:[0,1] op_sel_hi:[1,1]
	v_add_f32_e32 v198, v198, v199
	s_nop 0
	v_pk_mul_f32 v[212:213], v[150:151], v[158:159] op_sel:[0,1] op_sel_hi:[1,1]
	v_add_f32_dpp v198, v198, v198 quad_perm:[1,0,3,2] row_mask:0xf bank_mask:0xf bound_ctrl:1
	v_add_f32_dpp v207, v207, v207 quad_perm:[1,0,3,2] row_mask:0xf bank_mask:0xf bound_ctrl:1
	v_pk_mul_f32 v[250:251], v[152:153], v[158:159] op_sel:[0,1] op_sel_hi:[1,1]
	v_add_f32_dpp v198, v198, v198 quad_perm:[2,3,0,1] row_mask:0xf bank_mask:0xf bound_ctrl:1
	v_add_f32_dpp v207, v207, v207 quad_perm:[2,3,0,1] row_mask:0xf bank_mask:0xf bound_ctrl:1
	s_nop 0
	v_add_f32_dpp v198, v198, v198 row_half_mirror row_mask:0xf bank_mask:0xf bound_ctrl:1
	v_add_f32_dpp v207, v207, v207 row_half_mirror row_mask:0xf bank_mask:0xf bound_ctrl:1
	s_and_saveexec_b64 s[4:5], s[12:13]
	ds_write_b32 v162, v207 offset:1792
	s_mov_b64 exec, s[4:5]
	s_waitcnt lgkmcnt(5)
	v_pk_fma_f32 v[58:59], v[198:199], v[50:51], v[58:59] op_sel_hi:[0,1,1]
	v_pk_fma_f32 v[72:73], v[198:199], v[52:53], v[72:73] op_sel_hi:[0,1,1]
	s_waitcnt lgkmcnt(3)
	v_pk_fma_f32 v[66:67], v[66:67], v[42:43], v[58:59]
	v_pk_fma_f32 v[64:65], v[64:65], v[44:45], v[72:73]
	v_pk_fma_f32 v[212:213], v[198:199], v[54:55], v[212:213] op_sel_hi:[0,1,1]
	v_pk_fma_f32 v[250:251], v[198:199], v[56:57], v[250:251] op_sel_hi:[0,1,1]
	v_pk_fma_f32 v[62:63], v[62:63], v[46:47], v[212:213]
	v_pk_fma_f32 v[60:61], v[60:61], v[48:49], v[250:251]
	s_waitcnt lgkmcnt(1)
	v_pk_fma_f32 v[58:59], v[66:67], v[154:155], 0 op_sel_hi:[1,1,0]
	v_pk_fma_f32 v[72:73], v[64:65], v[156:157], 0 op_sel_hi:[1,1,0]
	v_pk_fma_f32 v[58:59], v[62:63], v[246:247], v[58:59]
	v_pk_fma_f32 v[72:73], v[60:61], v[248:249], v[72:73]
	v_add_f32_e32 v207, v58, v59
	v_add_f32_e32 v209, v72, v73
	v_add_f32_e32 v207, v207, v209
	s_nop 1
	v_add_f32_dpp v207, v207, v207 quad_perm:[1,0,3,2] row_mask:0xf bank_mask:0xf bound_ctrl:1
	s_nop 1
	v_add_f32_dpp v207, v207, v207 quad_perm:[2,3,0,1] row_mask:0xf bank_mask:0xf bound_ctrl:1
	s_nop 1
	v_add_f32_dpp v207, v207, v207 row_half_mirror row_mask:0xf bank_mask:0xf bound_ctrl:1
	s_and_saveexec_b64 s[4:5], s[12:13]
	ds_write_b32 v162, v207 offset:1920
	s_mov_b64 exec, s[4:5]
